# GEMM main loops: stage LDS-DMA loads use SGPR base + 32-bit VGPR offset instead of a 64-bit VGPR address (16 fewer v_lshl_add_u64 per iteration in the loader segments)
# speedup vs baseline: 1.0124x; 1.0124x over previous
; #define G_STAGE(bufoff, gbase) do { _Pragma("unroll") for (int _i = 0; _i < 2; ++_i) \
;         __builtin_amdgcn_global_load_lds((const unsigned*)((const char*)(gbase) + voff[_i]), (LAS unsigned*)(lds + (bufoff) + ldsw + _i * 8192), 16, 0, 0); } while (0)
; #define G_LDA(dst, b, h) do { _Pragma("unroll") for (int m = 0; m < 4; ++m) _Pragma("unroll") for (int k = 0; k < 2; ++k) dst[m][k] = *(const LAS bf16x8*)(lds + G_SA(b, h) + aoff + m * 2048 + k * 1024); } while (0)
; #define G_LDB(dst, b, h) do { _Pragma("unroll") for (int n = 0; n < 2; ++n) _Pragma("unroll") for (int k = 0; k < 2; ++k) dst[n][k] = *(const LAS bf16x8*)(lds + G_SB(b, h) + boff + n * 2048 + k * 1024); } while (0)
; #define G_MMA(ai, bj, At, Bt) do { __builtin_amdgcn_s_setprio(1); _Pragma("unroll") for (int m = 0; m < 4; ++m) _Pragma("unroll") for (int n = 0; n < 2; ++n) _Pragma("unroll") for (int k = 0; k < 2; ++k) \
;         acc[ai][bj][m][n] = MFMA16(Bt[n][k], At[m][k], acc[ai][bj][m][n]); __builtin_amdgcn_s_setprio(0); } while (0)
; #define G_WAIT_V(n) asm volatile("s_waitcnt vmcnt(" #n ")" ::: "memory")
; #define G_WAIT_L(n) asm volatile("s_waitcnt lgkmcnt(" #n ")" ::: "memory")
; #define G_BAR __builtin_amdgcn_s_barrier()
; #define G_SCHED __builtin_amdgcn_sched_barrier(0)
; template <class Epi>
; __device__ __forceinline__ void gemm_phase(LAS unsigned char* lds, const bf16_t* Ag, const bf16_t* Btg, const int K, const int nM, const int nN, const Epi& E) {
;     ...
;             G_LDB(B0, 0, 0); G_SCHED; G_LDA(At, 0, 0); G_STAGE(G_SA(1, 1), a1 + hstep);
;             G_WAIT_L(8); G_BAR; G_WAIT_L(0); G_MMA(0, 0, At, B0); G_BAR; G_SCHED;
;             G_LDB(B1, 0, 1); G_STAGE(G_SB(0, 0), b2);
;             G_BAR; G_WAIT_L(0); G_MMA(0, 1, At, B1); G_BAR;
;             G_LDA(At, 0, 1); G_STAGE(G_SA(0, 0), a2);
;             G_BAR; G_WAIT_L(0); G_MMA(1, 0, At, B0); G_BAR; G_SCHED;
;             G_STAGE(G_SB(0, 1), b2 + hstep);
;             G_WAIT_V(6); G_BAR; G_MMA(1, 1, At, B1); G_BAR;
.LBB0_78:
	s_add_u32 s12, s50, 0xfffc0080
	s_addc_u32 s26, s51, -1
	s_and_b64 s[52:53], s[52:53], exec
	s_cselect_b32 s55, s26, s43
	s_cselect_b32 s54, s12, s42
	s_cselect_b32 s53, s72, s15
	s_cselect_b32 s52, s71, s69
	s_add_i32 s12, 0, 0x10000
	v_add_u32_e32 v136, s12, v175
	ds_read_b128 v[124:127], v136
	ds_read_b128 v[128:131], v136 offset:1024
	ds_read_b128 v[132:135], v136 offset:2048
	ds_read_b128 v[136:139], v136 offset:3072
	s_add_i32 m0, s58, 0xc000
	ds_read_b128 v[140:143], v186
	ds_read_b128 v[148:151], v186 offset:1024
	ds_read_b128 v[152:155], v186 offset:2048
	ds_read_b128 v[156:159], v186 offset:3072
	ds_read_b128 v[188:191], v186 offset:4096
	ds_read_b128 v[192:195], v186 offset:5120
	ds_read_b128 v[222:225], v186 offset:6144
	ds_read_b128 v[226:229], v186 offset:7168
	global_load_lds_dwordx4 v170, s[50:51]
	s_add_i32 m0, s58, 0xe000
	s_nop 0
	global_load_lds_dwordx4 v168, s[50:51]
	s_waitcnt lgkmcnt(8)
	s_barrier
	s_waitcnt lgkmcnt(0)
	s_setprio 1
	s_waitcnt lgkmcnt(0)
	v_mfma_f32_16x16x32_bf16 v[164:167], v[124:127], v[140:143], v[164:167]
	v_mfma_f32_16x16x32_bf16 v[160:163], v[132:135], v[140:143], v[160:163]
	v_mfma_f32_16x16x32_bf16 v[116:119], v[124:127], v[152:155], v[116:119]
	v_mfma_f32_16x16x32_bf16 v[112:115], v[132:135], v[152:155], v[112:115]
	v_mfma_f32_16x16x32_bf16 v[100:103], v[124:127], v[188:191], v[100:103]
	v_mfma_f32_16x16x32_bf16 v[96:99], v[132:135], v[188:191], v[96:99]
	v_mfma_f32_16x16x32_bf16 v[84:87], v[124:127], v[222:225], v[84:87]
	v_mfma_f32_16x16x32_bf16 v[80:83], v[132:135], v[222:225], v[80:83]
	v_mfma_f32_16x16x32_bf16 v[164:167], v[128:131], v[148:151], v[164:167]
	v_mfma_f32_16x16x32_bf16 v[160:163], v[136:139], v[148:151], v[160:163]
	v_mfma_f32_16x16x32_bf16 v[116:119], v[128:131], v[156:159], v[116:119]
	v_mfma_f32_16x16x32_bf16 v[112:115], v[136:139], v[156:159], v[112:115]
	v_mfma_f32_16x16x32_bf16 v[100:103], v[128:131], v[192:195], v[100:103]
	v_mfma_f32_16x16x32_bf16 v[96:99], v[136:139], v[192:195], v[96:99]
	v_mfma_f32_16x16x32_bf16 v[84:87], v[128:131], v[226:229], v[84:87]
	v_mfma_f32_16x16x32_bf16 v[80:83], v[136:139], v[226:229], v[80:83]
	s_setprio 0
	s_barrier
	s_add_i32 s26, 0, 0x14000
	v_add_u32_e32 v172, s26, v175
	s_add_i32 s12, s12, s57
	ds_read_b128 v[230:233], v172
	ds_read_b128 v[234:237], v172 offset:1024
	ds_read_b128 v[238:241], v172 offset:2048
	ds_read_b128 v[242:245], v172 offset:3072
	s_mov_b32 m0, s12
	s_nop 0
	global_load_lds_dwordx4 v0, s[52:53]
	s_add_i32 m0, s12, 0x2000
	s_nop 0
	global_load_lds_dwordx4 v2, s[52:53]
	s_barrier
	s_waitcnt lgkmcnt(0)
	s_setprio 1
	s_waitcnt lgkmcnt(0)
	v_mfma_f32_16x16x32_bf16 v[144:147], v[230:233], v[140:143], v[144:147]
	v_mfma_f32_16x16x32_bf16 v[120:123], v[238:241], v[140:143], v[120:123]
	v_mfma_f32_16x16x32_bf16 v[108:111], v[230:233], v[152:155], v[108:111]
	v_mfma_f32_16x16x32_bf16 v[104:107], v[238:241], v[152:155], v[104:107]
	v_mfma_f32_16x16x32_bf16 v[92:95], v[230:233], v[188:191], v[92:95]
	v_mfma_f32_16x16x32_bf16 v[88:91], v[238:241], v[188:191], v[88:91]
	v_mfma_f32_16x16x32_bf16 v[76:79], v[230:233], v[222:225], v[76:79]
	v_mfma_f32_16x16x32_bf16 v[72:75], v[238:241], v[222:225], v[72:75]
	v_mfma_f32_16x16x32_bf16 v[144:147], v[234:237], v[148:151], v[144:147]
	v_mfma_f32_16x16x32_bf16 v[120:123], v[242:245], v[148:151], v[120:123]
	v_mfma_f32_16x16x32_bf16 v[108:111], v[234:237], v[156:159], v[108:111]
	v_mfma_f32_16x16x32_bf16 v[104:107], v[242:245], v[156:159], v[104:107]
	v_mfma_f32_16x16x32_bf16 v[92:95], v[234:237], v[192:195], v[92:95]
	v_mfma_f32_16x16x32_bf16 v[88:91], v[242:245], v[192:195], v[88:91]
	v_mfma_f32_16x16x32_bf16 v[76:79], v[234:237], v[226:229], v[76:79]
	v_mfma_f32_16x16x32_bf16 v[72:75], v[242:245], v[226:229], v[72:75]
	s_setprio 0
	s_mov_b32 m0, s58
	s_barrier
	ds_read_b128 v[140:143], v186 offset:16384
	ds_read_b128 v[148:151], v186 offset:17408
	ds_read_b128 v[152:155], v186 offset:18432
	ds_read_b128 v[156:159], v186 offset:19456
	ds_read_b128 v[188:191], v186 offset:20480
	ds_read_b128 v[192:195], v186 offset:21504
	ds_read_b128 v[222:225], v186 offset:22528
	ds_read_b128 v[226:229], v186 offset:23552
	global_load_lds_dwordx4 v0, s[54:55]
	s_mov_b32 m0, s59
	s_nop 0
	global_load_lds_dwordx4 v2, s[54:55]
	s_barrier
	s_waitcnt lgkmcnt(0)
	s_setprio 1
	s_waitcnt lgkmcnt(0)
	v_mfma_f32_16x16x32_bf16 v[60:63], v[124:127], v[140:143], v[60:63]
	v_mfma_f32_16x16x32_bf16 v[56:59], v[132:135], v[140:143], v[56:59]
	v_mfma_f32_16x16x32_bf16 v[44:47], v[124:127], v[152:155], v[44:47]
	v_mfma_f32_16x16x32_bf16 v[40:43], v[132:135], v[152:155], v[40:43]
	v_mfma_f32_16x16x32_bf16 v[28:31], v[124:127], v[188:191], v[28:31]
	v_mfma_f32_16x16x32_bf16 v[24:27], v[132:135], v[188:191], v[24:27]
	v_mfma_f32_16x16x32_bf16 v[12:15], v[124:127], v[222:225], v[12:15]
	v_mfma_f32_16x16x32_bf16 v[8:11], v[132:135], v[222:225], v[8:11]
	v_mfma_f32_16x16x32_bf16 v[60:63], v[128:131], v[148:151], v[60:63]
	v_mfma_f32_16x16x32_bf16 v[56:59], v[136:139], v[148:151], v[56:59]
	v_mfma_f32_16x16x32_bf16 v[44:47], v[128:131], v[156:159], v[44:47]
	v_mfma_f32_16x16x32_bf16 v[40:43], v[136:139], v[156:159], v[40:43]
	v_mfma_f32_16x16x32_bf16 v[28:31], v[128:131], v[192:195], v[28:31]
	v_mfma_f32_16x16x32_bf16 v[24:27], v[136:139], v[192:195], v[24:27]
	v_mfma_f32_16x16x32_bf16 v[12:15], v[128:131], v[226:229], v[12:15]
	v_mfma_f32_16x16x32_bf16 v[8:11], v[136:139], v[226:229], v[8:11]
	s_setprio 0
	s_barrier
	s_add_u32 s74, s52, 0x40000
	s_addc_u32 s75, s53, 0
	s_add_i32 s12, s26, s57
	s_mov_b32 m0, s12
	s_nop 0
	global_load_lds_dwordx4 v0, s[74:75]
	s_add_i32 m0, s12, 0x2000
	s_nop 0
	global_load_lds_dwordx4 v2, s[74:75]
	s_waitcnt vmcnt(6)
	s_barrier
; #define G_STAGE(bufoff, gbase) do { _Pragma("unroll") for (int _i = 0; _i < 2; ++_i) \
;         __builtin_amdgcn_global_load_lds((const unsigned*)((const char*)(gbase) + voff[_i]), (LAS unsigned*)(lds + (bufoff) + ldsw + _i * 8192), 16, 0, 0); } while (0)
; #define G_LDA(dst, b, h) do { _Pragma("unroll") for (int m = 0; m < 4; ++m) _Pragma("unroll") for (int k = 0; k < 2; ++k) dst[m][k] = *(const LAS bf16x8*)(lds + G_SA(b, h) + aoff + m * 2048 + k * 1024); } while (0)
; #define G_LDB(dst, b, h) do { _Pragma("unroll") for (int n = 0; n < 2; ++n) _Pragma("unroll") for (int k = 0; k < 2; ++k) dst[n][k] = *(const LAS bf16x8*)(lds + G_SB(b, h) + boff + n * 2048 + k * 1024); } while (0)
; #define G_MMA(ai, bj, At, Bt) do { __builtin_amdgcn_s_setprio(1); _Pragma("unroll") for (int m = 0; m < 4; ++m) _Pragma("unroll") for (int n = 0; n < 2; ++n) _Pragma("unroll") for (int k = 0; k < 2; ++k) \
;         acc[ai][bj][m][n] = MFMA16(Bt[n][k], At[m][k], acc[ai][bj][m][n]); __builtin_amdgcn_s_setprio(0); } while (0)
; #define G_WAIT_V(n) asm volatile("s_waitcnt vmcnt(" #n ")" ::: "memory")
; #define G_WAIT_L(n) asm volatile("s_waitcnt lgkmcnt(" #n ")" ::: "memory")
; #define G_BAR __builtin_amdgcn_s_barrier()
; #define G_SCHED __builtin_amdgcn_sched_barrier(0)
; template <class Epi>
; __device__ __forceinline__ void gemm_phase(LAS unsigned char* lds, const bf16_t* Ag, const bf16_t* Btg, const int K, const int nM, const int nN, const Epi& E) {
;     ...
;             G_WAIT_V(6); G_BAR; G_MMA(1, 1, At, B1); G_BAR;
;             G_LDB(B0, 1, 0); G_SCHED; G_LDA(At, 1, 0); G_STAGE(G_SA(0, 1), a2 + hstep);
;             G_WAIT_L(8); G_BAR; G_WAIT_L(0); G_MMA(0, 0, At, B0); G_BAR; G_SCHED;
;             G_LDB(B1, 1, 1); G_STAGE(G_SB(1, 0), b3);
;             G_BAR; G_WAIT_L(0); G_MMA(0, 1, At, B1); G_BAR;
;             G_LDA(At, 1, 1); G_STAGE(G_SA(1, 0), a3);
	s_setprio 1
	v_mfma_f32_16x16x32_bf16 v[68:71], v[230:233], v[140:143], v[68:71]
	v_mfma_f32_16x16x32_bf16 v[64:67], v[238:241], v[140:143], v[64:67]
	v_mfma_f32_16x16x32_bf16 v[52:55], v[230:233], v[152:155], v[52:55]
	v_mfma_f32_16x16x32_bf16 v[48:51], v[238:241], v[152:155], v[48:51]
	v_mfma_f32_16x16x32_bf16 v[36:39], v[230:233], v[188:191], v[36:39]
	v_mfma_f32_16x16x32_bf16 v[32:35], v[238:241], v[188:191], v[32:35]
	v_mfma_f32_16x16x32_bf16 v[20:23], v[230:233], v[222:225], v[20:23]
	v_mfma_f32_16x16x32_bf16 v[16:19], v[238:241], v[222:225], v[16:19]
	v_mfma_f32_16x16x32_bf16 v[68:71], v[234:237], v[148:151], v[68:71]
	v_mfma_f32_16x16x32_bf16 v[64:67], v[242:245], v[148:151], v[64:67]
	v_mfma_f32_16x16x32_bf16 v[52:55], v[234:237], v[156:159], v[52:55]
	v_mfma_f32_16x16x32_bf16 v[48:51], v[242:245], v[156:159], v[48:51]
	v_mfma_f32_16x16x32_bf16 v[36:39], v[234:237], v[192:195], v[36:39]
	v_mfma_f32_16x16x32_bf16 v[32:35], v[242:245], v[192:195], v[32:35]
	v_mfma_f32_16x16x32_bf16 v[20:23], v[234:237], v[226:229], v[20:23]
	v_mfma_f32_16x16x32_bf16 v[16:19], v[242:245], v[226:229], v[16:19]
	s_setprio 0
	s_add_i32 s12, 0, 0x18000
	v_add_u32_e32 v136, s12, v175
	s_barrier
	ds_read_b128 v[124:127], v136
	ds_read_b128 v[128:131], v136 offset:1024
	ds_read_b128 v[132:135], v136 offset:2048
	ds_read_b128 v[136:139], v136 offset:3072
	s_add_u32 s54, s54, 0x40000
	s_addc_u32 s55, s55, 0
	s_mov_b32 m0, s60
	ds_read_b128 v[140:143], v186 offset:32768
	ds_read_b128 v[148:151], v186 offset:33792
	ds_read_b128 v[152:155], v186 offset:34816
	ds_read_b128 v[156:159], v186 offset:35840
	ds_read_b128 v[188:191], v186 offset:36864
	ds_read_b128 v[192:195], v186 offset:37888
	ds_read_b128 v[222:225], v186 offset:38912
	ds_read_b128 v[226:229], v186 offset:39936
	global_load_lds_dwordx4 v0, s[54:55]
	s_mov_b32 m0, s61
	s_nop 0
	global_load_lds_dwordx4 v2, s[54:55]
	s_waitcnt lgkmcnt(8)
	s_barrier
	s_waitcnt lgkmcnt(0)
	s_setprio 1
	s_waitcnt lgkmcnt(0)
	v_mfma_f32_16x16x32_bf16 v[164:167], v[124:127], v[140:143], v[164:167]
	v_mfma_f32_16x16x32_bf16 v[160:163], v[132:135], v[140:143], v[160:163]
	v_mfma_f32_16x16x32_bf16 v[116:119], v[124:127], v[152:155], v[116:119]
	v_mfma_f32_16x16x32_bf16 v[112:115], v[132:135], v[152:155], v[112:115]
	v_mfma_f32_16x16x32_bf16 v[100:103], v[124:127], v[188:191], v[100:103]
	v_mfma_f32_16x16x32_bf16 v[96:99], v[132:135], v[188:191], v[96:99]
	v_mfma_f32_16x16x32_bf16 v[84:87], v[124:127], v[222:225], v[84:87]
	v_mfma_f32_16x16x32_bf16 v[80:83], v[132:135], v[222:225], v[80:83]
	v_mfma_f32_16x16x32_bf16 v[164:167], v[128:131], v[148:151], v[164:167]
	v_mfma_f32_16x16x32_bf16 v[160:163], v[136:139], v[148:151], v[160:163]
	v_mfma_f32_16x16x32_bf16 v[116:119], v[128:131], v[156:159], v[116:119]
	v_mfma_f32_16x16x32_bf16 v[112:115], v[136:139], v[156:159], v[112:115]
	v_mfma_f32_16x16x32_bf16 v[100:103], v[128:131], v[192:195], v[100:103]
	v_mfma_f32_16x16x32_bf16 v[96:99], v[136:139], v[192:195], v[96:99]
	v_mfma_f32_16x16x32_bf16 v[84:87], v[128:131], v[226:229], v[84:87]
	v_mfma_f32_16x16x32_bf16 v[80:83], v[136:139], v[226:229], v[80:83]
	s_setprio 0
	s_barrier
	s_add_i32 s26, 0, 0x1c000
	s_add_i32 s12, s12, s57
	v_add_u32_e32 v187, s26, v175
	s_mov_b32 m0, s12
	ds_read_b128 v[230:233], v187
	ds_read_b128 v[234:237], v187 offset:1024
	ds_read_b128 v[238:241], v187 offset:2048
	ds_read_b128 v[242:245], v187 offset:3072
	s_add_u32 s98, s52, 0x80
	s_addc_u32 s99, s53, 0
	global_load_lds_dwordx4 v0, s[98:99]
	s_add_i32 m0, s12, 0x2000
	s_nop 0
	s_add_u32 s98, s52, 0x80
	s_addc_u32 s99, s53, 0
	global_load_lds_dwordx4 v2, s[98:99]
	s_barrier
; #define G_STAGE(bufoff, gbase) do { _Pragma("unroll") for (int _i = 0; _i < 2; ++_i) \
;         __builtin_amdgcn_global_load_lds((const unsigned*)((const char*)(gbase) + voff[_i]), (LAS unsigned*)(lds + (bufoff) + ldsw + _i * 8192), 16, 0, 0); } while (0)
; #define G_LDA(dst, b, h) do { _Pragma("unroll") for (int m = 0; m < 4; ++m) _Pragma("unroll") for (int k = 0; k < 2; ++k) dst[m][k] = *(const LAS bf16x8*)(lds + G_SA(b, h) + aoff + m * 2048 + k * 1024); } while (0)
; #define G_MMA(ai, bj, At, Bt) do { __builtin_amdgcn_s_setprio(1); _Pragma("unroll") for (int m = 0; m < 4; ++m) _Pragma("unroll") for (int n = 0; n < 2; ++n) _Pragma("unroll") for (int k = 0; k < 2; ++k) \
;         acc[ai][bj][m][n] = MFMA16(Bt[n][k], At[m][k], acc[ai][bj][m][n]); __builtin_amdgcn_s_setprio(0); } while (0)
; #define G_WAIT_V(n) asm volatile("s_waitcnt vmcnt(" #n ")" ::: "memory")
; #define G_WAIT_L(n) asm volatile("s_waitcnt lgkmcnt(" #n ")" ::: "memory")
; #define G_BAR __builtin_amdgcn_s_barrier()
; #define G_SCHED __builtin_amdgcn_sched_barrier(0)
; template <class Epi>
; __device__ __forceinline__ void gemm_phase(LAS unsigned char* lds, const bf16_t* Ag, const bf16_t* Btg, const int K, const int nM, const int nN, const Epi& E) {
;     ...
;             G_BAR; G_WAIT_L(0); G_MMA(0, 1, At, B1); G_BAR;
;             G_LDA(At, 1, 1); G_STAGE(G_SA(1, 0), a3);
;             G_BAR; G_WAIT_L(0); G_MMA(1, 0, At, B0); G_BAR; G_SCHED;
;             G_STAGE(G_SB(1, 1), b3 + hstep);
;             G_WAIT_V(6); G_BAR; G_MMA(1, 1, At, B1); G_BAR;
;         }
	s_waitcnt lgkmcnt(0)
	s_setprio 1
	s_waitcnt lgkmcnt(0)
	v_mfma_f32_16x16x32_bf16 v[144:147], v[230:233], v[140:143], v[144:147]
	v_mfma_f32_16x16x32_bf16 v[120:123], v[238:241], v[140:143], v[120:123]
	v_mfma_f32_16x16x32_bf16 v[108:111], v[230:233], v[152:155], v[108:111]
	v_mfma_f32_16x16x32_bf16 v[104:107], v[238:241], v[152:155], v[104:107]
	v_mfma_f32_16x16x32_bf16 v[92:95], v[230:233], v[188:191], v[92:95]
	v_mfma_f32_16x16x32_bf16 v[88:91], v[238:241], v[188:191], v[88:91]
	v_mfma_f32_16x16x32_bf16 v[76:79], v[230:233], v[222:225], v[76:79]
	v_mfma_f32_16x16x32_bf16 v[72:75], v[238:241], v[222:225], v[72:75]
	v_mfma_f32_16x16x32_bf16 v[144:147], v[234:237], v[148:151], v[144:147]
	v_mfma_f32_16x16x32_bf16 v[120:123], v[242:245], v[148:151], v[120:123]
	v_mfma_f32_16x16x32_bf16 v[108:111], v[234:237], v[156:159], v[108:111]
	v_mfma_f32_16x16x32_bf16 v[104:107], v[242:245], v[156:159], v[104:107]
	v_mfma_f32_16x16x32_bf16 v[92:95], v[234:237], v[192:195], v[92:95]
	v_mfma_f32_16x16x32_bf16 v[88:91], v[242:245], v[192:195], v[88:91]
	v_mfma_f32_16x16x32_bf16 v[76:79], v[234:237], v[226:229], v[76:79]
	v_mfma_f32_16x16x32_bf16 v[72:75], v[242:245], v[226:229], v[72:75]
	s_setprio 0
	s_mov_b32 m0, s62
	s_barrier
	ds_read_b128 v[140:143], v186 offset:49152
	ds_read_b128 v[148:151], v186 offset:50176
	ds_read_b128 v[152:155], v186 offset:51200
	ds_read_b128 v[156:159], v186 offset:52224
	ds_read_b128 v[188:191], v186 offset:53248
	ds_read_b128 v[192:195], v186 offset:54272
	ds_read_b128 v[222:225], v186 offset:55296
	ds_read_b128 v[226:229], v186 offset:56320
	s_add_u32 s98, s54, 0xfffc0080
	s_addc_u32 s99, s55, -1
	global_load_lds_dwordx4 v0, s[98:99]
	s_mov_b32 m0, s63
	s_nop 0
	s_add_u32 s98, s54, 0xfffc0080
	s_addc_u32 s99, s55, -1
	global_load_lds_dwordx4 v2, s[98:99]
	s_barrier
	s_waitcnt lgkmcnt(0)
	s_setprio 1
	s_waitcnt lgkmcnt(0)
	v_mfma_f32_16x16x32_bf16 v[60:63], v[124:127], v[140:143], v[60:63]
	v_mfma_f32_16x16x32_bf16 v[56:59], v[132:135], v[140:143], v[56:59]
	v_mfma_f32_16x16x32_bf16 v[44:47], v[124:127], v[152:155], v[44:47]
	v_mfma_f32_16x16x32_bf16 v[40:43], v[132:135], v[152:155], v[40:43]
	v_mfma_f32_16x16x32_bf16 v[28:31], v[124:127], v[188:191], v[28:31]
	v_mfma_f32_16x16x32_bf16 v[24:27], v[132:135], v[188:191], v[24:27]
	v_mfma_f32_16x16x32_bf16 v[12:15], v[124:127], v[222:225], v[12:15]
	v_mfma_f32_16x16x32_bf16 v[8:11], v[132:135], v[222:225], v[8:11]
	v_mfma_f32_16x16x32_bf16 v[60:63], v[128:131], v[148:151], v[60:63]
	v_mfma_f32_16x16x32_bf16 v[56:59], v[136:139], v[148:151], v[56:59]
	v_mfma_f32_16x16x32_bf16 v[44:47], v[128:131], v[156:159], v[44:47]
	v_mfma_f32_16x16x32_bf16 v[40:43], v[136:139], v[156:159], v[40:43]
	v_mfma_f32_16x16x32_bf16 v[28:31], v[128:131], v[192:195], v[28:31]
	v_mfma_f32_16x16x32_bf16 v[24:27], v[136:139], v[192:195], v[24:27]
	v_mfma_f32_16x16x32_bf16 v[12:15], v[128:131], v[226:229], v[12:15]
	v_mfma_f32_16x16x32_bf16 v[8:11], v[136:139], v[226:229], v[8:11]
	s_setprio 0
	s_barrier
	s_add_u32 s52, s52, 0x40080
	s_addc_u32 s53, s53, 0
	s_add_i32 s12, s26, s57
	s_mov_b32 m0, s12
	s_nop 0
	global_load_lds_dwordx4 v0, s[52:53]
	s_add_i32 m0, s12, 0x2000
	s_nop 0
	global_load_lds_dwordx4 v2, s[52:53]
	s_waitcnt vmcnt(6)
	s_barrier
	s_setprio 1
	v_mfma_f32_16x16x32_bf16 v[68:71], v[230:233], v[140:143], v[68:71]
	v_mfma_f32_16x16x32_bf16 v[64:67], v[238:241], v[140:143], v[64:67]
	v_mfma_f32_16x16x32_bf16 v[52:55], v[230:233], v[152:155], v[52:55]
	v_mfma_f32_16x16x32_bf16 v[48:51], v[238:241], v[152:155], v[48:51]
	v_mfma_f32_16x16x32_bf16 v[36:39], v[230:233], v[188:191], v[36:39]
	v_mfma_f32_16x16x32_bf16 v[32:35], v[238:241], v[188:191], v[32:35]
	v_mfma_f32_16x16x32_bf16 v[20:23], v[230:233], v[222:225], v[20:23]
	v_mfma_f32_16x16x32_bf16 v[16:19], v[238:241], v[222:225], v[16:19]
	v_mfma_f32_16x16x32_bf16 v[68:71], v[234:237], v[148:151], v[68:71]
	v_mfma_f32_16x16x32_bf16 v[64:67], v[242:245], v[148:151], v[64:67]
	v_mfma_f32_16x16x32_bf16 v[52:55], v[234:237], v[156:159], v[52:55]
	v_mfma_f32_16x16x32_bf16 v[48:51], v[242:245], v[156:159], v[48:51]
	v_mfma_f32_16x16x32_bf16 v[36:39], v[234:237], v[192:195], v[36:39]
	v_mfma_f32_16x16x32_bf16 v[32:35], v[242:245], v[192:195], v[32:35]
	v_mfma_f32_16x16x32_bf16 v[20:23], v[234:237], v[226:229], v[20:23]
	v_mfma_f32_16x16x32_bf16 v[16:19], v[242:245], v[226:229], v[16:19]
	s_setprio 0
	s_add_i32 s73, s73, 2
	s_add_u32 s71, s71, 0x100
	s_addc_u32 s72, s72, 0
	s_add_u32 s50, s50, 0x100
	s_addc_u32 s51, s51, 0
	s_cmp_gt_u32 s73, 13
	s_barrier
	s_cbranch_scc1 .LBB0_82

;     __device__ __forceinline__ void prep(int pm, int par, LAS unsigned char* lds) const { if (fold) prep_rowstats(stat, pm, par, lds); }
;     __device__ __forceinline__ void prep(int pm, int par, LAS unsigned char* lds) const { if (!ident) prep_rowstats(stat, pm, par, lds); }
;     __device__ __forceinline__ void prep(int pm, int par, LAS unsigned char* lds) const { prep_rowstats(stat, pm, par, lds); }
; #define G_STAGE(bufoff, gbase) do { _Pragma("unroll") for (int _i = 0; _i < 2; ++_i) \
;         __builtin_amdgcn_global_load_lds((const unsigned*)((const char*)(gbase) + voff[_i]), (LAS unsigned*)(lds + (bufoff) + ldsw + _i * 8192), 16, 0, 0); } while (0)
; #define G_LDA(dst, b, h) do { _Pragma("unroll") for (int m = 0; m < 4; ++m) _Pragma("unroll") for (int k = 0; k < 2; ++k) dst[m][k] = *(const LAS bf16x8*)(lds + G_SA(b, h) + aoff + m * 2048 + k * 1024); } while (0)
; #define G_LDB(dst, b, h) do { _Pragma("unroll") for (int n = 0; n < 2; ++n) _Pragma("unroll") for (int k = 0; k < 2; ++k) dst[n][k] = *(const LAS bf16x8*)(lds + G_SB(b, h) + boff + n * 2048 + k * 1024); } while (0)
; #define G_WAIT_V(n) asm volatile("s_waitcnt vmcnt(" #n ")" ::: "memory")
; #define G_WAIT_L(n) asm volatile("s_waitcnt lgkmcnt(" #n ")" ::: "memory")
; template <class Epi>
; __device__ __forceinline__ void gemm_phase(LAS unsigned char* lds, const bf16_t* Ag, const bf16_t* Btg, const int K, const int nM, const int nN, const Epi& E) {
;     ...
;         for (int t = 0; t < nt; t += 2) {
;             const bool last = (t == nt - 2);
;             const char* a1 = cA + (size_t)(t + 1) * kstep;
;             const char* a2 = last ? nA : cA + (size_t)(t + 2) * kstep; const char* b2 = last ? nB : cB + (size_t)(t + 2) * kstep;
;             const char* a3 = a2 + kstep; const char* b3 = b2 + kstep;
;             if (last && has_next && pmn != pm) E.prep(pmn, par ^ 1, lds);
;             G_LDB(B0, 0, 0); G_SCHED; G_LDA(At, 0, 0); G_STAGE(G_SA(1, 1), a1 + hstep);
;             G_WAIT_L(8); G_BAR; G_WAIT_L(0); G_MMA(0, 0, At, B0); G_BAR; G_SCHED;
;             G_LDB(B1, 0, 1); G_STAGE(G_SB(0, 0), b2);
;             G_BAR; G_WAIT_L(0); G_MMA(0, 1, At, B1); G_BAR;
;             G_LDA(At, 0, 1); G_STAGE(G_SA(0, 0), a2);
;             G_BAR; G_WAIT_L(0); G_MMA(1, 0, At, B0); G_BAR; G_SCHED;
;             G_STAGE(G_SB(0, 1), b2 + hstep);
;             G_WAIT_V(6); G_BAR; G_MMA(1, 1, At, B1); G_BAR;
.LBB0_153:
	s_add_u32 s66, s64, 0x100
	s_addc_u32 s67, s65, 0
	s_and_b64 s[68:69], s[68:69], exec
	s_cselect_b32 s71, s67, s55
	s_cselect_b32 s70, s66, s54
	s_cselect_b32 s69, s61, s14
	s_cselect_b32 s68, s57, s15
	s_add_i32 s12, 0, 0x10000
	v_add_u32_e32 v141, s12, v179
	ds_read_b128 v[144:147], v141
	ds_read_b128 v[148:151], v141 offset:1024
	ds_read_b128 v[152:155], v141 offset:2048
	ds_read_b128 v[156:159], v141 offset:3072
	s_add_i32 m0, s72, 0xc000
	ds_read_b128 v[160:163], v230
	ds_read_b128 v[164:167], v230 offset:1024
	ds_read_b128 v[168:171], v230 offset:2048
	ds_read_b128 v[172:175], v230 offset:3072
	ds_read_b128 v[180:183], v230 offset:4096
	ds_read_b128 v[184:187], v230 offset:5120
	ds_read_b128 v[188:191], v230 offset:6144
	ds_read_b128 v[192:195], v230 offset:7168
	global_load_lds_dwordx4 v138, s[64:65]
	s_add_i32 m0, s72, 0xe000
	s_nop 0
	global_load_lds_dwordx4 v136, s[64:65]
	s_waitcnt lgkmcnt(8)
	s_barrier
	s_waitcnt lgkmcnt(0)
	s_setprio 1
	s_waitcnt lgkmcnt(0)
	v_mfma_f32_16x16x32_bf16 v[132:135], v[144:147], v[160:163], v[132:135]
	v_mfma_f32_16x16x32_bf16 v[128:131], v[152:155], v[160:163], v[128:131]
	v_mfma_f32_16x16x32_bf16 v[116:119], v[144:147], v[168:171], v[116:119]
	v_mfma_f32_16x16x32_bf16 v[112:115], v[152:155], v[168:171], v[112:115]
	v_mfma_f32_16x16x32_bf16 v[100:103], v[144:147], v[180:183], v[100:103]
	v_mfma_f32_16x16x32_bf16 v[96:99], v[152:155], v[180:183], v[96:99]
	v_mfma_f32_16x16x32_bf16 v[84:87], v[144:147], v[188:191], v[84:87]
	v_mfma_f32_16x16x32_bf16 v[80:83], v[152:155], v[188:191], v[80:83]
	v_mfma_f32_16x16x32_bf16 v[132:135], v[148:151], v[164:167], v[132:135]
	v_mfma_f32_16x16x32_bf16 v[128:131], v[156:159], v[164:167], v[128:131]
	v_mfma_f32_16x16x32_bf16 v[116:119], v[148:151], v[172:175], v[116:119]
	v_mfma_f32_16x16x32_bf16 v[112:115], v[156:159], v[172:175], v[112:115]
	v_mfma_f32_16x16x32_bf16 v[100:103], v[148:151], v[184:187], v[100:103]
	v_mfma_f32_16x16x32_bf16 v[96:99], v[156:159], v[184:187], v[96:99]
	v_mfma_f32_16x16x32_bf16 v[84:87], v[148:151], v[192:195], v[84:87]
	v_mfma_f32_16x16x32_bf16 v[80:83], v[156:159], v[192:195], v[80:83]
	s_setprio 0
	s_barrier
	s_add_i32 s26, 0, 0x14000
	s_add_i32 s12, s12, s21
	v_add_u32_e32 v141, s26, v179
	s_mov_b32 m0, s12
	ds_read_b128 v[232:235], v141
	ds_read_b128 v[236:239], v141 offset:1024
	ds_read_b128 v[240:243], v141 offset:2048
	ds_read_b128 v[244:247], v141 offset:3072
	global_load_lds_dwordx4 v0, s[68:69]
	s_add_i32 m0, s12, 0x2000
	s_nop 0
	global_load_lds_dwordx4 v2, s[68:69]
	s_barrier
	s_waitcnt lgkmcnt(0)
	s_setprio 1
	s_waitcnt lgkmcnt(0)
	v_mfma_f32_16x16x32_bf16 v[124:127], v[232:235], v[160:163], v[124:127]
	v_mfma_f32_16x16x32_bf16 v[120:123], v[240:243], v[160:163], v[120:123]
	v_mfma_f32_16x16x32_bf16 v[108:111], v[232:235], v[168:171], v[108:111]
	v_mfma_f32_16x16x32_bf16 v[104:107], v[240:243], v[168:171], v[104:107]
	v_mfma_f32_16x16x32_bf16 v[92:95], v[232:235], v[180:183], v[92:95]
	v_mfma_f32_16x16x32_bf16 v[88:91], v[240:243], v[180:183], v[88:91]
	v_mfma_f32_16x16x32_bf16 v[76:79], v[232:235], v[188:191], v[76:79]
	v_mfma_f32_16x16x32_bf16 v[72:75], v[240:243], v[188:191], v[72:75]
	v_mfma_f32_16x16x32_bf16 v[124:127], v[236:239], v[164:167], v[124:127]
	v_mfma_f32_16x16x32_bf16 v[120:123], v[244:247], v[164:167], v[120:123]
	v_mfma_f32_16x16x32_bf16 v[108:111], v[236:239], v[172:175], v[108:111]
	v_mfma_f32_16x16x32_bf16 v[104:107], v[244:247], v[172:175], v[104:107]
	v_mfma_f32_16x16x32_bf16 v[92:95], v[236:239], v[184:187], v[92:95]
	v_mfma_f32_16x16x32_bf16 v[88:91], v[244:247], v[184:187], v[88:91]
	v_mfma_f32_16x16x32_bf16 v[76:79], v[236:239], v[192:195], v[76:79]
	v_mfma_f32_16x16x32_bf16 v[72:75], v[244:247], v[192:195], v[72:75]
	s_setprio 0
	s_mov_b32 m0, s72
	s_barrier
	ds_read_b128 v[160:163], v230 offset:16384
	ds_read_b128 v[164:167], v230 offset:17408
	ds_read_b128 v[168:171], v230 offset:18432
	ds_read_b128 v[172:175], v230 offset:19456
	ds_read_b128 v[180:183], v230 offset:20480
	ds_read_b128 v[184:187], v230 offset:21504
	ds_read_b128 v[188:191], v230 offset:22528
	ds_read_b128 v[192:195], v230 offset:23552
	global_load_lds_dwordx4 v0, s[70:71]
	s_mov_b32 m0, s73
	s_nop 0
	global_load_lds_dwordx4 v2, s[70:71]
	s_barrier
	s_waitcnt lgkmcnt(0)
	s_setprio 1
	s_waitcnt lgkmcnt(0)
	v_mfma_f32_16x16x32_bf16 v[68:71], v[144:147], v[160:163], v[68:71]
	v_mfma_f32_16x16x32_bf16 v[64:67], v[152:155], v[160:163], v[64:67]
	v_mfma_f32_16x16x32_bf16 v[52:55], v[144:147], v[168:171], v[52:55]
	v_mfma_f32_16x16x32_bf16 v[48:51], v[152:155], v[168:171], v[48:51]
	v_mfma_f32_16x16x32_bf16 v[36:39], v[144:147], v[180:183], v[36:39]
	v_mfma_f32_16x16x32_bf16 v[32:35], v[152:155], v[180:183], v[32:35]
	v_mfma_f32_16x16x32_bf16 v[20:23], v[144:147], v[188:191], v[20:23]
	v_mfma_f32_16x16x32_bf16 v[16:19], v[152:155], v[188:191], v[16:19]
	v_mfma_f32_16x16x32_bf16 v[68:71], v[148:151], v[164:167], v[68:71]
	v_mfma_f32_16x16x32_bf16 v[64:67], v[156:159], v[164:167], v[64:67]
	v_mfma_f32_16x16x32_bf16 v[52:55], v[148:151], v[172:175], v[52:55]
	v_mfma_f32_16x16x32_bf16 v[48:51], v[156:159], v[172:175], v[48:51]
	v_mfma_f32_16x16x32_bf16 v[36:39], v[148:151], v[184:187], v[36:39]
	v_mfma_f32_16x16x32_bf16 v[32:35], v[156:159], v[184:187], v[32:35]
	v_mfma_f32_16x16x32_bf16 v[20:23], v[148:151], v[192:195], v[20:23]
	v_mfma_f32_16x16x32_bf16 v[16:19], v[156:159], v[192:195], v[16:19]
	s_setprio 0
	s_barrier
	s_add_u32 s64, s68, 0x40000
	s_addc_u32 s65, s69, 0
	s_add_i32 s12, s26, s21
	s_mov_b32 m0, s12
	s_nop 0
	global_load_lds_dwordx4 v0, s[64:65]
	s_add_i32 m0, s12, 0x2000
	s_nop 0
	global_load_lds_dwordx4 v2, s[64:65]
	s_waitcnt vmcnt(6)
	s_barrier
; #define G_STAGE(bufoff, gbase) do { _Pragma("unroll") for (int _i = 0; _i < 2; ++_i) \
;         __builtin_amdgcn_global_load_lds((const unsigned*)((const char*)(gbase) + voff[_i]), (LAS unsigned*)(lds + (bufoff) + ldsw + _i * 8192), 16, 0, 0); } while (0)
; #define G_LDA(dst, b, h) do { _Pragma("unroll") for (int m = 0; m < 4; ++m) _Pragma("unroll") for (int k = 0; k < 2; ++k) dst[m][k] = *(const LAS bf16x8*)(lds + G_SA(b, h) + aoff + m * 2048 + k * 1024); } while (0)
; #define G_LDB(dst, b, h) do { _Pragma("unroll") for (int n = 0; n < 2; ++n) _Pragma("unroll") for (int k = 0; k < 2; ++k) dst[n][k] = *(const LAS bf16x8*)(lds + G_SB(b, h) + boff + n * 2048 + k * 1024); } while (0)
; #define G_MMA(ai, bj, At, Bt) do { __builtin_amdgcn_s_setprio(1); _Pragma("unroll") for (int m = 0; m < 4; ++m) _Pragma("unroll") for (int n = 0; n < 2; ++n) _Pragma("unroll") for (int k = 0; k < 2; ++k) \
;         acc[ai][bj][m][n] = MFMA16(Bt[n][k], At[m][k], acc[ai][bj][m][n]); __builtin_amdgcn_s_setprio(0); } while (0)
; #define G_WAIT_V(n) asm volatile("s_waitcnt vmcnt(" #n ")" ::: "memory")
; #define G_WAIT_L(n) asm volatile("s_waitcnt lgkmcnt(" #n ")" ::: "memory")
; #define G_BAR __builtin_amdgcn_s_barrier()
; #define G_SCHED __builtin_amdgcn_sched_barrier(0)
; template <class Epi>
; __device__ __forceinline__ void gemm_phase(LAS unsigned char* lds, const bf16_t* Ag, const bf16_t* Btg, const int K, const int nM, const int nN, const Epi& E) {
;     ...
;             G_WAIT_V(6); G_BAR; G_MMA(1, 1, At, B1); G_BAR;
;             G_LDB(B0, 1, 0); G_SCHED; G_LDA(At, 1, 0); G_STAGE(G_SA(0, 1), a2 + hstep);
;             G_WAIT_L(8); G_BAR; G_WAIT_L(0); G_MMA(0, 0, At, B0); G_BAR; G_SCHED;
;             G_LDB(B1, 1, 1); G_STAGE(G_SB(1, 0), b3);
;             G_BAR; G_WAIT_L(0); G_MMA(0, 1, At, B1); G_BAR;
;             G_LDA(At, 1, 1); G_STAGE(G_SA(1, 0), a3);
	s_setprio 1
	v_mfma_f32_16x16x32_bf16 v[60:63], v[232:235], v[160:163], v[60:63]
	v_mfma_f32_16x16x32_bf16 v[56:59], v[240:243], v[160:163], v[56:59]
	v_mfma_f32_16x16x32_bf16 v[44:47], v[232:235], v[168:171], v[44:47]
	v_mfma_f32_16x16x32_bf16 v[40:43], v[240:243], v[168:171], v[40:43]
	v_mfma_f32_16x16x32_bf16 v[28:31], v[232:235], v[180:183], v[28:31]
	v_mfma_f32_16x16x32_bf16 v[24:27], v[240:243], v[180:183], v[24:27]
	v_mfma_f32_16x16x32_bf16 v[12:15], v[232:235], v[188:191], v[12:15]
	v_mfma_f32_16x16x32_bf16 v[8:11], v[240:243], v[188:191], v[8:11]
	v_mfma_f32_16x16x32_bf16 v[60:63], v[236:239], v[164:167], v[60:63]
	v_mfma_f32_16x16x32_bf16 v[56:59], v[244:247], v[164:167], v[56:59]
	v_mfma_f32_16x16x32_bf16 v[44:47], v[236:239], v[172:175], v[44:47]
	v_mfma_f32_16x16x32_bf16 v[40:43], v[244:247], v[172:175], v[40:43]
	v_mfma_f32_16x16x32_bf16 v[28:31], v[236:239], v[184:187], v[28:31]
	v_mfma_f32_16x16x32_bf16 v[24:27], v[244:247], v[184:187], v[24:27]
	v_mfma_f32_16x16x32_bf16 v[12:15], v[236:239], v[192:195], v[12:15]
	v_mfma_f32_16x16x32_bf16 v[8:11], v[244:247], v[192:195], v[8:11]
	s_setprio 0
	s_add_i32 s12, 0, 0x18000
	v_add_u32_e32 v141, s12, v179
	s_barrier
	ds_read_b128 v[144:147], v141
	ds_read_b128 v[148:151], v141 offset:1024
	ds_read_b128 v[152:155], v141 offset:2048
	ds_read_b128 v[156:159], v141 offset:3072
	s_add_u32 s64, s70, 0x40000
	s_addc_u32 s65, s71, 0
	s_mov_b32 m0, s74
	ds_read_b128 v[160:163], v230 offset:32768
	ds_read_b128 v[164:167], v230 offset:33792
	ds_read_b128 v[168:171], v230 offset:34816
	ds_read_b128 v[172:175], v230 offset:35840
	ds_read_b128 v[180:183], v230 offset:36864
	ds_read_b128 v[184:187], v230 offset:37888
	ds_read_b128 v[188:191], v230 offset:38912
	ds_read_b128 v[192:195], v230 offset:39936
	global_load_lds_dwordx4 v0, s[64:65]
	s_mov_b32 m0, s75
	s_nop 0
	global_load_lds_dwordx4 v2, s[64:65]
	s_waitcnt lgkmcnt(8)
	s_barrier
	s_waitcnt lgkmcnt(0)
	s_setprio 1
	s_waitcnt lgkmcnt(0)
	v_mfma_f32_16x16x32_bf16 v[132:135], v[144:147], v[160:163], v[132:135]
	v_mfma_f32_16x16x32_bf16 v[128:131], v[152:155], v[160:163], v[128:131]
	v_mfma_f32_16x16x32_bf16 v[116:119], v[144:147], v[168:171], v[116:119]
	v_mfma_f32_16x16x32_bf16 v[112:115], v[152:155], v[168:171], v[112:115]
	v_mfma_f32_16x16x32_bf16 v[100:103], v[144:147], v[180:183], v[100:103]
	v_mfma_f32_16x16x32_bf16 v[96:99], v[152:155], v[180:183], v[96:99]
	v_mfma_f32_16x16x32_bf16 v[84:87], v[144:147], v[188:191], v[84:87]
	v_mfma_f32_16x16x32_bf16 v[80:83], v[152:155], v[188:191], v[80:83]
	v_mfma_f32_16x16x32_bf16 v[132:135], v[148:151], v[164:167], v[132:135]
	v_mfma_f32_16x16x32_bf16 v[128:131], v[156:159], v[164:167], v[128:131]
	v_mfma_f32_16x16x32_bf16 v[116:119], v[148:151], v[172:175], v[116:119]
	v_mfma_f32_16x16x32_bf16 v[112:115], v[156:159], v[172:175], v[112:115]
	v_mfma_f32_16x16x32_bf16 v[100:103], v[148:151], v[184:187], v[100:103]
	v_mfma_f32_16x16x32_bf16 v[96:99], v[156:159], v[184:187], v[96:99]
	v_mfma_f32_16x16x32_bf16 v[84:87], v[148:151], v[192:195], v[84:87]
	v_mfma_f32_16x16x32_bf16 v[80:83], v[156:159], v[192:195], v[80:83]
	s_setprio 0
	s_barrier
	s_add_i32 s26, 0, 0x1c000
	s_add_i32 s12, s12, s21
	v_add_u32_e32 v141, s26, v179
	s_mov_b32 m0, s12
	ds_read_b128 v[232:235], v141
	ds_read_b128 v[236:239], v141 offset:1024
	ds_read_b128 v[240:243], v141 offset:2048
	ds_read_b128 v[244:247], v141 offset:3072
	s_add_u32 s98, s68, 0x80
	s_addc_u32 s99, s69, 0
	global_load_lds_dwordx4 v0, s[98:99]
	s_add_i32 m0, s12, 0x2000
	s_nop 0
	s_add_u32 s98, s68, 0x80
	s_addc_u32 s99, s69, 0
	global_load_lds_dwordx4 v2, s[98:99]
	s_barrier
; #define G_STAGE(bufoff, gbase) do { _Pragma("unroll") for (int _i = 0; _i < 2; ++_i) \
;         __builtin_amdgcn_global_load_lds((const unsigned*)((const char*)(gbase) + voff[_i]), (LAS unsigned*)(lds + (bufoff) + ldsw + _i * 8192), 16, 0, 0); } while (0)
; #define G_LDA(dst, b, h) do { _Pragma("unroll") for (int m = 0; m < 4; ++m) _Pragma("unroll") for (int k = 0; k < 2; ++k) dst[m][k] = *(const LAS bf16x8*)(lds + G_SA(b, h) + aoff + m * 2048 + k * 1024); } while (0)
; #define G_MMA(ai, bj, At, Bt) do { __builtin_amdgcn_s_setprio(1); _Pragma("unroll") for (int m = 0; m < 4; ++m) _Pragma("unroll") for (int n = 0; n < 2; ++n) _Pragma("unroll") for (int k = 0; k < 2; ++k) \
;         acc[ai][bj][m][n] = MFMA16(Bt[n][k], At[m][k], acc[ai][bj][m][n]); __builtin_amdgcn_s_setprio(0); } while (0)
; #define G_WAIT_V(n) asm volatile("s_waitcnt vmcnt(" #n ")" ::: "memory")
; #define G_WAIT_L(n) asm volatile("s_waitcnt lgkmcnt(" #n ")" ::: "memory")
; #define G_BAR __builtin_amdgcn_s_barrier()
; #define G_SCHED __builtin_amdgcn_sched_barrier(0)
; template <class Epi>
; __device__ __forceinline__ void gemm_phase(LAS unsigned char* lds, const bf16_t* Ag, const bf16_t* Btg, const int K, const int nM, const int nN, const Epi& E) {
;     ...
;             G_BAR; G_WAIT_L(0); G_MMA(0, 1, At, B1); G_BAR;
;             G_LDA(At, 1, 1); G_STAGE(G_SA(1, 0), a3);
;             G_BAR; G_WAIT_L(0); G_MMA(1, 0, At, B0); G_BAR; G_SCHED;
;             G_STAGE(G_SB(1, 1), b3 + hstep);
;             G_WAIT_V(6); G_BAR; G_MMA(1, 1, At, B1); G_BAR;
;         }
	s_waitcnt lgkmcnt(0)
	s_setprio 1
	s_waitcnt lgkmcnt(0)
	v_mfma_f32_16x16x32_bf16 v[124:127], v[232:235], v[160:163], v[124:127]
	v_mfma_f32_16x16x32_bf16 v[120:123], v[240:243], v[160:163], v[120:123]
	v_mfma_f32_16x16x32_bf16 v[108:111], v[232:235], v[168:171], v[108:111]
	v_mfma_f32_16x16x32_bf16 v[104:107], v[240:243], v[168:171], v[104:107]
	v_mfma_f32_16x16x32_bf16 v[92:95], v[232:235], v[180:183], v[92:95]
	v_mfma_f32_16x16x32_bf16 v[88:91], v[240:243], v[180:183], v[88:91]
	v_mfma_f32_16x16x32_bf16 v[76:79], v[232:235], v[188:191], v[76:79]
	v_mfma_f32_16x16x32_bf16 v[72:75], v[240:243], v[188:191], v[72:75]
	v_mfma_f32_16x16x32_bf16 v[124:127], v[236:239], v[164:167], v[124:127]
	v_mfma_f32_16x16x32_bf16 v[120:123], v[244:247], v[164:167], v[120:123]
	v_mfma_f32_16x16x32_bf16 v[108:111], v[236:239], v[172:175], v[108:111]
	v_mfma_f32_16x16x32_bf16 v[104:107], v[244:247], v[172:175], v[104:107]
	v_mfma_f32_16x16x32_bf16 v[92:95], v[236:239], v[184:187], v[92:95]
	v_mfma_f32_16x16x32_bf16 v[88:91], v[244:247], v[184:187], v[88:91]
	v_mfma_f32_16x16x32_bf16 v[76:79], v[236:239], v[192:195], v[76:79]
	v_mfma_f32_16x16x32_bf16 v[72:75], v[244:247], v[192:195], v[72:75]
	s_setprio 0
	s_mov_b32 m0, s76
	s_barrier
	ds_read_b128 v[160:163], v230 offset:49152
	ds_read_b128 v[164:167], v230 offset:50176
	ds_read_b128 v[168:171], v230 offset:51200
	ds_read_b128 v[172:175], v230 offset:52224
	ds_read_b128 v[180:183], v230 offset:53248
	ds_read_b128 v[184:187], v230 offset:54272
	ds_read_b128 v[188:191], v230 offset:55296
	ds_read_b128 v[192:195], v230 offset:56320
	s_add_u32 s98, s70, 0x80
	s_addc_u32 s99, s71, 0
	global_load_lds_dwordx4 v0, s[98:99]
	s_mov_b32 m0, s77
	s_nop 0
	s_add_u32 s98, s70, 0x80
	s_addc_u32 s99, s71, 0
	global_load_lds_dwordx4 v2, s[98:99]
	s_barrier
	s_waitcnt lgkmcnt(0)
	s_setprio 1
	s_waitcnt lgkmcnt(0)
	v_mfma_f32_16x16x32_bf16 v[68:71], v[144:147], v[160:163], v[68:71]
	v_mfma_f32_16x16x32_bf16 v[64:67], v[152:155], v[160:163], v[64:67]
	v_mfma_f32_16x16x32_bf16 v[52:55], v[144:147], v[168:171], v[52:55]
	v_mfma_f32_16x16x32_bf16 v[48:51], v[152:155], v[168:171], v[48:51]
	v_mfma_f32_16x16x32_bf16 v[36:39], v[144:147], v[180:183], v[36:39]
	v_mfma_f32_16x16x32_bf16 v[32:35], v[152:155], v[180:183], v[32:35]
	v_mfma_f32_16x16x32_bf16 v[20:23], v[144:147], v[188:191], v[20:23]
	v_mfma_f32_16x16x32_bf16 v[16:19], v[152:155], v[188:191], v[16:19]
	v_mfma_f32_16x16x32_bf16 v[68:71], v[148:151], v[164:167], v[68:71]
	v_mfma_f32_16x16x32_bf16 v[64:67], v[156:159], v[164:167], v[64:67]
	v_mfma_f32_16x16x32_bf16 v[52:55], v[148:151], v[172:175], v[52:55]
	v_mfma_f32_16x16x32_bf16 v[48:51], v[156:159], v[172:175], v[48:51]
	v_mfma_f32_16x16x32_bf16 v[36:39], v[148:151], v[184:187], v[36:39]
	v_mfma_f32_16x16x32_bf16 v[32:35], v[156:159], v[184:187], v[32:35]
	v_mfma_f32_16x16x32_bf16 v[20:23], v[148:151], v[192:195], v[20:23]
	v_mfma_f32_16x16x32_bf16 v[16:19], v[156:159], v[192:195], v[16:19]
	s_setprio 0
	s_barrier
	s_add_u32 s64, s68, 0x40080
	s_addc_u32 s65, s69, 0
	s_add_i32 s12, s26, s21
	s_mov_b32 m0, s12
	s_nop 0
	global_load_lds_dwordx4 v0, s[64:65]
	s_add_i32 m0, s12, 0x2000
	s_nop 0
	global_load_lds_dwordx4 v2, s[64:65]
	s_waitcnt vmcnt(6)
	s_barrier
	s_setprio 1
	v_mfma_f32_16x16x32_bf16 v[60:63], v[232:235], v[160:163], v[60:63]
	v_mfma_f32_16x16x32_bf16 v[56:59], v[240:243], v[160:163], v[56:59]
	v_mfma_f32_16x16x32_bf16 v[44:47], v[232:235], v[168:171], v[44:47]
	v_mfma_f32_16x16x32_bf16 v[40:43], v[240:243], v[168:171], v[40:43]
	v_mfma_f32_16x16x32_bf16 v[28:31], v[232:235], v[180:183], v[28:31]
	v_mfma_f32_16x16x32_bf16 v[24:27], v[240:243], v[180:183], v[24:27]
	v_mfma_f32_16x16x32_bf16 v[12:15], v[232:235], v[188:191], v[12:15]
	v_mfma_f32_16x16x32_bf16 v[8:11], v[240:243], v[188:191], v[8:11]
	v_mfma_f32_16x16x32_bf16 v[60:63], v[236:239], v[164:167], v[60:63]
	v_mfma_f32_16x16x32_bf16 v[56:59], v[244:247], v[164:167], v[56:59]
	v_mfma_f32_16x16x32_bf16 v[44:47], v[236:239], v[172:175], v[44:47]
	v_mfma_f32_16x16x32_bf16 v[40:43], v[244:247], v[172:175], v[40:43]
	v_mfma_f32_16x16x32_bf16 v[28:31], v[236:239], v[184:187], v[28:31]
	v_mfma_f32_16x16x32_bf16 v[24:27], v[244:247], v[184:187], v[24:27]
	v_mfma_f32_16x16x32_bf16 v[12:15], v[236:239], v[192:195], v[12:15]
	v_mfma_f32_16x16x32_bf16 v[8:11], v[244:247], v[192:195], v[8:11]
	s_setprio 0
	s_add_i32 s42, s42, 2
	s_add_u32 s57, s57, 0x100
	s_addc_u32 s61, s61, 0
	s_cmp_gt_u32 s42, 13
	s_mov_b64 s[64:65], s[66:67]
	s_barrier
	s_cbranch_scc1 .LBB0_157

;     __device__ __forceinline__ void prep(int pm, int par, LAS unsigned char* lds) const { if (fold) prep_rowstats(stat, pm, par, lds); }
;     __device__ __forceinline__ void prep(int pm, int par, LAS unsigned char* lds) const { if (!ident) prep_rowstats(stat, pm, par, lds); }
;     __device__ __forceinline__ void prep(int pm, int par, LAS unsigned char* lds) const { prep_rowstats(stat, pm, par, lds); }
; #define G_STAGE(bufoff, gbase) do { _Pragma("unroll") for (int _i = 0; _i < 2; ++_i) \
;         __builtin_amdgcn_global_load_lds((const unsigned*)((const char*)(gbase) + voff[_i]), (LAS unsigned*)(lds + (bufoff) + ldsw + _i * 8192), 16, 0, 0); } while (0)
; #define G_LDA(dst, b, h) do { _Pragma("unroll") for (int m = 0; m < 4; ++m) _Pragma("unroll") for (int k = 0; k < 2; ++k) dst[m][k] = *(const LAS bf16x8*)(lds + G_SA(b, h) + aoff + m * 2048 + k * 1024); } while (0)
; #define G_LDB(dst, b, h) do { _Pragma("unroll") for (int n = 0; n < 2; ++n) _Pragma("unroll") for (int k = 0; k < 2; ++k) dst[n][k] = *(const LAS bf16x8*)(lds + G_SB(b, h) + boff + n * 2048 + k * 1024); } while (0)
; #define G_WAIT_V(n) asm volatile("s_waitcnt vmcnt(" #n ")" ::: "memory")
; #define G_WAIT_L(n) asm volatile("s_waitcnt lgkmcnt(" #n ")" ::: "memory")
; template <class Epi>
; __device__ __forceinline__ void gemm_phase(LAS unsigned char* lds, const bf16_t* Ag, const bf16_t* Btg, const int K, const int nM, const int nN, const Epi& E) {
;     ...
;         for (int t = 0; t < nt; t += 2) {
;             const bool last = (t == nt - 2);
;             const char* a1 = cA + (size_t)(t + 1) * kstep;
;             const char* a2 = last ? nA : cA + (size_t)(t + 2) * kstep; const char* b2 = last ? nB : cB + (size_t)(t + 2) * kstep;
;             const char* a3 = a2 + kstep; const char* b3 = b2 + kstep;
;             if (last && has_next && pmn != pm) E.prep(pmn, par ^ 1, lds);
;             G_LDB(B0, 0, 0); G_SCHED; G_LDA(At, 0, 0); G_STAGE(G_SA(1, 1), a1 + hstep);
;             G_WAIT_L(8); G_BAR; G_WAIT_L(0); G_MMA(0, 0, At, B0); G_BAR; G_SCHED;
;             G_LDB(B1, 0, 1); G_STAGE(G_SB(0, 0), b2);
;             G_BAR; G_WAIT_L(0); G_MMA(0, 1, At, B1); G_BAR;
;             G_LDA(At, 0, 1); G_STAGE(G_SA(0, 0), a2);
;             G_BAR; G_WAIT_L(0); G_MMA(1, 0, At, B0); G_BAR; G_SCHED;
;             G_STAGE(G_SB(0, 1), b2 + hstep);
;             G_WAIT_V(6); G_BAR; G_MMA(1, 1, At, B1); G_BAR;
.LBB0_744:
	s_add_u32 s58, s56, 0x100
	s_addc_u32 s59, s57, 0
	s_and_b64 s[60:61], s[60:61], exec
	s_cselect_b32 s63, s59, s47
	s_cselect_b32 s62, s58, s46
	s_cselect_b32 s61, s78, s15
	s_cselect_b32 s60, s77, s49
	s_add_i32 s12, 0, 0x10000
	v_add_u32_e32 v152, s12, v165
	ds_read_b128 v[140:143], v152
	ds_read_b128 v[144:147], v152 offset:1024
	ds_read_b128 v[148:151], v152 offset:2048
	ds_read_b128 v[152:155], v152 offset:3072
	s_add_i32 m0, s66, 0xc000
	ds_read_b128 v[156:159], v174
	ds_read_b128 v[160:163], v174 offset:1024
	ds_read_b128 v[180:183], v174 offset:2048
	ds_read_b128 v[184:187], v174 offset:3072
	ds_read_b128 v[188:191], v174 offset:4096
	ds_read_b128 v[192:195], v174 offset:5120
	ds_read_b128 v[222:225], v174 offset:6144
	ds_read_b128 v[226:229], v174 offset:7168
	global_load_lds_dwordx4 v138, s[56:57]
	s_add_i32 m0, s66, 0xe000
	s_nop 0
	global_load_lds_dwordx4 v136, s[56:57]
	s_waitcnt lgkmcnt(8)
	s_barrier
	s_waitcnt lgkmcnt(0)
	s_setprio 1
	s_waitcnt lgkmcnt(0)
	v_mfma_f32_16x16x32_bf16 v[132:135], v[140:143], v[156:159], v[132:135]
	v_mfma_f32_16x16x32_bf16 v[128:131], v[148:151], v[156:159], v[128:131]
	v_mfma_f32_16x16x32_bf16 v[116:119], v[140:143], v[180:183], v[116:119]
	v_mfma_f32_16x16x32_bf16 v[112:115], v[148:151], v[180:183], v[112:115]
	v_mfma_f32_16x16x32_bf16 v[100:103], v[140:143], v[188:191], v[100:103]
	v_mfma_f32_16x16x32_bf16 v[96:99], v[148:151], v[188:191], v[96:99]
	v_mfma_f32_16x16x32_bf16 v[84:87], v[140:143], v[222:225], v[84:87]
	v_mfma_f32_16x16x32_bf16 v[80:83], v[148:151], v[222:225], v[80:83]
	v_mfma_f32_16x16x32_bf16 v[132:135], v[144:147], v[160:163], v[132:135]
	v_mfma_f32_16x16x32_bf16 v[128:131], v[152:155], v[160:163], v[128:131]
	v_mfma_f32_16x16x32_bf16 v[116:119], v[144:147], v[184:187], v[116:119]
	v_mfma_f32_16x16x32_bf16 v[112:115], v[152:155], v[184:187], v[112:115]
	v_mfma_f32_16x16x32_bf16 v[100:103], v[144:147], v[192:195], v[100:103]
	v_mfma_f32_16x16x32_bf16 v[96:99], v[152:155], v[192:195], v[96:99]
	v_mfma_f32_16x16x32_bf16 v[84:87], v[144:147], v[226:229], v[84:87]
	v_mfma_f32_16x16x32_bf16 v[80:83], v[152:155], v[226:229], v[80:83]
	s_setprio 0
	s_barrier
	s_add_i32 s26, 0, 0x14000
	s_add_i32 s12, s12, s65
	v_add_u32_e32 v175, s26, v165
	s_mov_b32 m0, s12
	ds_read_b128 v[230:233], v175
	ds_read_b128 v[234:237], v175 offset:1024
	ds_read_b128 v[238:241], v175 offset:2048
	ds_read_b128 v[242:245], v175 offset:3072
	global_load_lds_dwordx4 v0, s[60:61]
	s_add_i32 m0, s12, 0x2000
	s_nop 0
	global_load_lds_dwordx4 v2, s[60:61]
	s_barrier
	s_waitcnt lgkmcnt(0)
	s_setprio 1
	s_waitcnt lgkmcnt(0)
	v_mfma_f32_16x16x32_bf16 v[124:127], v[230:233], v[156:159], v[124:127]
	v_mfma_f32_16x16x32_bf16 v[120:123], v[238:241], v[156:159], v[120:123]
	v_mfma_f32_16x16x32_bf16 v[108:111], v[230:233], v[180:183], v[108:111]
	v_mfma_f32_16x16x32_bf16 v[104:107], v[238:241], v[180:183], v[104:107]
	v_mfma_f32_16x16x32_bf16 v[92:95], v[230:233], v[188:191], v[92:95]
	v_mfma_f32_16x16x32_bf16 v[88:91], v[238:241], v[188:191], v[88:91]
	v_mfma_f32_16x16x32_bf16 v[76:79], v[230:233], v[222:225], v[76:79]
	v_mfma_f32_16x16x32_bf16 v[72:75], v[238:241], v[222:225], v[72:75]
	v_mfma_f32_16x16x32_bf16 v[124:127], v[234:237], v[160:163], v[124:127]
	v_mfma_f32_16x16x32_bf16 v[120:123], v[242:245], v[160:163], v[120:123]
	v_mfma_f32_16x16x32_bf16 v[108:111], v[234:237], v[184:187], v[108:111]
	v_mfma_f32_16x16x32_bf16 v[104:107], v[242:245], v[184:187], v[104:107]
	v_mfma_f32_16x16x32_bf16 v[92:95], v[234:237], v[192:195], v[92:95]
	v_mfma_f32_16x16x32_bf16 v[88:91], v[242:245], v[192:195], v[88:91]
	v_mfma_f32_16x16x32_bf16 v[76:79], v[234:237], v[226:229], v[76:79]
	v_mfma_f32_16x16x32_bf16 v[72:75], v[242:245], v[226:229], v[72:75]
	s_setprio 0
	s_mov_b32 m0, s66
	s_barrier
	ds_read_b128 v[156:159], v174 offset:16384
	ds_read_b128 v[160:163], v174 offset:17408
	ds_read_b128 v[180:183], v174 offset:18432
	ds_read_b128 v[184:187], v174 offset:19456
	ds_read_b128 v[188:191], v174 offset:20480
	ds_read_b128 v[192:195], v174 offset:21504
	ds_read_b128 v[222:225], v174 offset:22528
	ds_read_b128 v[226:229], v174 offset:23552
	global_load_lds_dwordx4 v0, s[62:63]
	s_mov_b32 m0, s67
	s_nop 0
	global_load_lds_dwordx4 v2, s[62:63]
	s_barrier
	s_waitcnt lgkmcnt(0)
	s_setprio 1
	s_waitcnt lgkmcnt(0)
	v_mfma_f32_16x16x32_bf16 v[68:71], v[140:143], v[156:159], v[68:71]
	v_mfma_f32_16x16x32_bf16 v[64:67], v[148:151], v[156:159], v[64:67]
	v_mfma_f32_16x16x32_bf16 v[52:55], v[140:143], v[180:183], v[52:55]
	v_mfma_f32_16x16x32_bf16 v[48:51], v[148:151], v[180:183], v[48:51]
	v_mfma_f32_16x16x32_bf16 v[36:39], v[140:143], v[188:191], v[36:39]
	v_mfma_f32_16x16x32_bf16 v[32:35], v[148:151], v[188:191], v[32:35]
	v_mfma_f32_16x16x32_bf16 v[20:23], v[140:143], v[222:225], v[20:23]
	v_mfma_f32_16x16x32_bf16 v[16:19], v[148:151], v[222:225], v[16:19]
	v_mfma_f32_16x16x32_bf16 v[68:71], v[144:147], v[160:163], v[68:71]
	v_mfma_f32_16x16x32_bf16 v[64:67], v[152:155], v[160:163], v[64:67]
	v_mfma_f32_16x16x32_bf16 v[52:55], v[144:147], v[184:187], v[52:55]
	v_mfma_f32_16x16x32_bf16 v[48:51], v[152:155], v[184:187], v[48:51]
	v_mfma_f32_16x16x32_bf16 v[36:39], v[144:147], v[192:195], v[36:39]
	v_mfma_f32_16x16x32_bf16 v[32:35], v[152:155], v[192:195], v[32:35]
	v_mfma_f32_16x16x32_bf16 v[20:23], v[144:147], v[226:229], v[20:23]
	v_mfma_f32_16x16x32_bf16 v[16:19], v[152:155], v[226:229], v[16:19]
	s_setprio 0
	s_barrier
	s_add_u32 s56, s60, 0x100000
	s_addc_u32 s57, s61, 0
	s_add_i32 s12, s26, s65
	s_mov_b32 m0, s12
	s_nop 0
	global_load_lds_dwordx4 v0, s[56:57]
	s_add_i32 m0, s12, 0x2000
	s_nop 0
	global_load_lds_dwordx4 v2, s[56:57]
	s_waitcnt vmcnt(6)
	s_barrier
; #define G_STAGE(bufoff, gbase) do { _Pragma("unroll") for (int _i = 0; _i < 2; ++_i) \
;         __builtin_amdgcn_global_load_lds((const unsigned*)((const char*)(gbase) + voff[_i]), (LAS unsigned*)(lds + (bufoff) + ldsw + _i * 8192), 16, 0, 0); } while (0)
; #define G_LDA(dst, b, h) do { _Pragma("unroll") for (int m = 0; m < 4; ++m) _Pragma("unroll") for (int k = 0; k < 2; ++k) dst[m][k] = *(const LAS bf16x8*)(lds + G_SA(b, h) + aoff + m * 2048 + k * 1024); } while (0)
; #define G_LDB(dst, b, h) do { _Pragma("unroll") for (int n = 0; n < 2; ++n) _Pragma("unroll") for (int k = 0; k < 2; ++k) dst[n][k] = *(const LAS bf16x8*)(lds + G_SB(b, h) + boff + n * 2048 + k * 1024); } while (0)
; #define G_MMA(ai, bj, At, Bt) do { __builtin_amdgcn_s_setprio(1); _Pragma("unroll") for (int m = 0; m < 4; ++m) _Pragma("unroll") for (int n = 0; n < 2; ++n) _Pragma("unroll") for (int k = 0; k < 2; ++k) \
;         acc[ai][bj][m][n] = MFMA16(Bt[n][k], At[m][k], acc[ai][bj][m][n]); __builtin_amdgcn_s_setprio(0); } while (0)
; #define G_WAIT_V(n) asm volatile("s_waitcnt vmcnt(" #n ")" ::: "memory")
; #define G_WAIT_L(n) asm volatile("s_waitcnt lgkmcnt(" #n ")" ::: "memory")
; #define G_BAR __builtin_amdgcn_s_barrier()
; #define G_SCHED __builtin_amdgcn_sched_barrier(0)
; template <class Epi>
; __device__ __forceinline__ void gemm_phase(LAS unsigned char* lds, const bf16_t* Ag, const bf16_t* Btg, const int K, const int nM, const int nN, const Epi& E) {
;     ...
;             G_WAIT_V(6); G_BAR; G_MMA(1, 1, At, B1); G_BAR;
;             G_LDB(B0, 1, 0); G_SCHED; G_LDA(At, 1, 0); G_STAGE(G_SA(0, 1), a2 + hstep);
;             G_WAIT_L(8); G_BAR; G_WAIT_L(0); G_MMA(0, 0, At, B0); G_BAR; G_SCHED;
;             G_LDB(B1, 1, 1); G_STAGE(G_SB(1, 0), b3);
;             G_BAR; G_WAIT_L(0); G_MMA(0, 1, At, B1); G_BAR;
;             G_LDA(At, 1, 1); G_STAGE(G_SA(1, 0), a3);
	s_setprio 1
	v_mfma_f32_16x16x32_bf16 v[60:63], v[230:233], v[156:159], v[60:63]
	v_mfma_f32_16x16x32_bf16 v[56:59], v[238:241], v[156:159], v[56:59]
	v_mfma_f32_16x16x32_bf16 v[44:47], v[230:233], v[180:183], v[44:47]
	v_mfma_f32_16x16x32_bf16 v[40:43], v[238:241], v[180:183], v[40:43]
	v_mfma_f32_16x16x32_bf16 v[28:31], v[230:233], v[188:191], v[28:31]
	v_mfma_f32_16x16x32_bf16 v[24:27], v[238:241], v[188:191], v[24:27]
	v_mfma_f32_16x16x32_bf16 v[12:15], v[230:233], v[222:225], v[12:15]
	v_mfma_f32_16x16x32_bf16 v[8:11], v[238:241], v[222:225], v[8:11]
	v_mfma_f32_16x16x32_bf16 v[60:63], v[234:237], v[160:163], v[60:63]
	v_mfma_f32_16x16x32_bf16 v[56:59], v[242:245], v[160:163], v[56:59]
	v_mfma_f32_16x16x32_bf16 v[44:47], v[234:237], v[184:187], v[44:47]
	v_mfma_f32_16x16x32_bf16 v[40:43], v[242:245], v[184:187], v[40:43]
	v_mfma_f32_16x16x32_bf16 v[28:31], v[234:237], v[192:195], v[28:31]
	v_mfma_f32_16x16x32_bf16 v[24:27], v[242:245], v[192:195], v[24:27]
	v_mfma_f32_16x16x32_bf16 v[12:15], v[234:237], v[226:229], v[12:15]
	v_mfma_f32_16x16x32_bf16 v[8:11], v[242:245], v[226:229], v[8:11]
	s_setprio 0
	s_add_i32 s12, 0, 0x18000
	v_add_u32_e32 v152, s12, v165
	s_barrier
	ds_read_b128 v[140:143], v152
	ds_read_b128 v[144:147], v152 offset:1024
	ds_read_b128 v[148:151], v152 offset:2048
	ds_read_b128 v[152:155], v152 offset:3072
	s_add_u32 s56, s62, 0x100000
	s_addc_u32 s57, s63, 0
	s_mov_b32 m0, s68
	ds_read_b128 v[156:159], v174 offset:32768
	ds_read_b128 v[160:163], v174 offset:33792
	ds_read_b128 v[180:183], v174 offset:34816
	ds_read_b128 v[184:187], v174 offset:35840
	ds_read_b128 v[188:191], v174 offset:36864
	ds_read_b128 v[192:195], v174 offset:37888
	ds_read_b128 v[222:225], v174 offset:38912
	ds_read_b128 v[226:229], v174 offset:39936
	global_load_lds_dwordx4 v0, s[56:57]
	s_mov_b32 m0, s69
	s_nop 0
	global_load_lds_dwordx4 v2, s[56:57]
	s_waitcnt lgkmcnt(8)
	s_barrier
	s_waitcnt lgkmcnt(0)
	s_setprio 1
	s_waitcnt lgkmcnt(0)
	v_mfma_f32_16x16x32_bf16 v[132:135], v[140:143], v[156:159], v[132:135]
	v_mfma_f32_16x16x32_bf16 v[128:131], v[148:151], v[156:159], v[128:131]
	v_mfma_f32_16x16x32_bf16 v[116:119], v[140:143], v[180:183], v[116:119]
	v_mfma_f32_16x16x32_bf16 v[112:115], v[148:151], v[180:183], v[112:115]
	v_mfma_f32_16x16x32_bf16 v[100:103], v[140:143], v[188:191], v[100:103]
	v_mfma_f32_16x16x32_bf16 v[96:99], v[148:151], v[188:191], v[96:99]
	v_mfma_f32_16x16x32_bf16 v[84:87], v[140:143], v[222:225], v[84:87]
	v_mfma_f32_16x16x32_bf16 v[80:83], v[148:151], v[222:225], v[80:83]
	v_mfma_f32_16x16x32_bf16 v[132:135], v[144:147], v[160:163], v[132:135]
	v_mfma_f32_16x16x32_bf16 v[128:131], v[152:155], v[160:163], v[128:131]
	v_mfma_f32_16x16x32_bf16 v[116:119], v[144:147], v[184:187], v[116:119]
	v_mfma_f32_16x16x32_bf16 v[112:115], v[152:155], v[184:187], v[112:115]
	v_mfma_f32_16x16x32_bf16 v[100:103], v[144:147], v[192:195], v[100:103]
	v_mfma_f32_16x16x32_bf16 v[96:99], v[152:155], v[192:195], v[96:99]
	v_mfma_f32_16x16x32_bf16 v[84:87], v[144:147], v[226:229], v[84:87]
	v_mfma_f32_16x16x32_bf16 v[80:83], v[152:155], v[226:229], v[80:83]
	s_setprio 0
	s_barrier
	s_add_i32 s26, 0, 0x1c000
	s_add_i32 s12, s12, s65
	v_add_u32_e32 v175, s26, v165
	s_mov_b32 m0, s12
	ds_read_b128 v[230:233], v175
	ds_read_b128 v[234:237], v175 offset:1024
	ds_read_b128 v[238:241], v175 offset:2048
	ds_read_b128 v[242:245], v175 offset:3072
	s_add_u32 s98, s60, 0x80
	s_addc_u32 s99, s61, 0
	global_load_lds_dwordx4 v0, s[98:99]
	s_add_i32 m0, s12, 0x2000
	s_nop 0
	s_add_u32 s98, s60, 0x80
	s_addc_u32 s99, s61, 0
	global_load_lds_dwordx4 v2, s[98:99]
	s_barrier
; #define G_STAGE(bufoff, gbase) do { _Pragma("unroll") for (int _i = 0; _i < 2; ++_i) \
;         __builtin_amdgcn_global_load_lds((const unsigned*)((const char*)(gbase) + voff[_i]), (LAS unsigned*)(lds + (bufoff) + ldsw + _i * 8192), 16, 0, 0); } while (0)
; #define G_LDA(dst, b, h) do { _Pragma("unroll") for (int m = 0; m < 4; ++m) _Pragma("unroll") for (int k = 0; k < 2; ++k) dst[m][k] = *(const LAS bf16x8*)(lds + G_SA(b, h) + aoff + m * 2048 + k * 1024); } while (0)
; #define G_MMA(ai, bj, At, Bt) do { __builtin_amdgcn_s_setprio(1); _Pragma("unroll") for (int m = 0; m < 4; ++m) _Pragma("unroll") for (int n = 0; n < 2; ++n) _Pragma("unroll") for (int k = 0; k < 2; ++k) \
;         acc[ai][bj][m][n] = MFMA16(Bt[n][k], At[m][k], acc[ai][bj][m][n]); __builtin_amdgcn_s_setprio(0); } while (0)
; #define G_WAIT_V(n) asm volatile("s_waitcnt vmcnt(" #n ")" ::: "memory")
; #define G_WAIT_L(n) asm volatile("s_waitcnt lgkmcnt(" #n ")" ::: "memory")
; #define G_BAR __builtin_amdgcn_s_barrier()
; #define G_SCHED __builtin_amdgcn_sched_barrier(0)
; template <class Epi>
; __device__ __forceinline__ void gemm_phase(LAS unsigned char* lds, const bf16_t* Ag, const bf16_t* Btg, const int K, const int nM, const int nN, const Epi& E) {
;     ...
;             G_BAR; G_WAIT_L(0); G_MMA(0, 1, At, B1); G_BAR;
;             G_LDA(At, 1, 1); G_STAGE(G_SA(1, 0), a3);
;             G_BAR; G_WAIT_L(0); G_MMA(1, 0, At, B0); G_BAR; G_SCHED;
;             G_STAGE(G_SB(1, 1), b3 + hstep);
;             G_WAIT_V(6); G_BAR; G_MMA(1, 1, At, B1); G_BAR;
;         }
	s_waitcnt lgkmcnt(0)
	s_setprio 1
	s_waitcnt lgkmcnt(0)
	v_mfma_f32_16x16x32_bf16 v[124:127], v[230:233], v[156:159], v[124:127]
	v_mfma_f32_16x16x32_bf16 v[120:123], v[238:241], v[156:159], v[120:123]
	v_mfma_f32_16x16x32_bf16 v[108:111], v[230:233], v[180:183], v[108:111]
	v_mfma_f32_16x16x32_bf16 v[104:107], v[238:241], v[180:183], v[104:107]
	v_mfma_f32_16x16x32_bf16 v[92:95], v[230:233], v[188:191], v[92:95]
	v_mfma_f32_16x16x32_bf16 v[88:91], v[238:241], v[188:191], v[88:91]
	v_mfma_f32_16x16x32_bf16 v[76:79], v[230:233], v[222:225], v[76:79]
	v_mfma_f32_16x16x32_bf16 v[72:75], v[238:241], v[222:225], v[72:75]
	v_mfma_f32_16x16x32_bf16 v[124:127], v[234:237], v[160:163], v[124:127]
	v_mfma_f32_16x16x32_bf16 v[120:123], v[242:245], v[160:163], v[120:123]
	v_mfma_f32_16x16x32_bf16 v[108:111], v[234:237], v[184:187], v[108:111]
	v_mfma_f32_16x16x32_bf16 v[104:107], v[242:245], v[184:187], v[104:107]
	v_mfma_f32_16x16x32_bf16 v[92:95], v[234:237], v[192:195], v[92:95]
	v_mfma_f32_16x16x32_bf16 v[88:91], v[242:245], v[192:195], v[88:91]
	v_mfma_f32_16x16x32_bf16 v[76:79], v[234:237], v[226:229], v[76:79]
	v_mfma_f32_16x16x32_bf16 v[72:75], v[242:245], v[226:229], v[72:75]
	s_setprio 0
	s_mov_b32 m0, s70
	s_barrier
	ds_read_b128 v[156:159], v174 offset:49152
	ds_read_b128 v[160:163], v174 offset:50176
	ds_read_b128 v[180:183], v174 offset:51200
	ds_read_b128 v[184:187], v174 offset:52224
	ds_read_b128 v[188:191], v174 offset:53248
	ds_read_b128 v[192:195], v174 offset:54272
	ds_read_b128 v[222:225], v174 offset:55296
	ds_read_b128 v[226:229], v174 offset:56320
	s_add_u32 s98, s62, 0x80
	s_addc_u32 s99, s63, 0
	global_load_lds_dwordx4 v0, s[98:99]
	s_mov_b32 m0, s71
	s_nop 0
	s_add_u32 s98, s62, 0x80
	s_addc_u32 s99, s63, 0
	global_load_lds_dwordx4 v2, s[98:99]
	s_barrier
	s_waitcnt lgkmcnt(0)
	s_setprio 1
	s_waitcnt lgkmcnt(0)
	v_mfma_f32_16x16x32_bf16 v[68:71], v[140:143], v[156:159], v[68:71]
	v_mfma_f32_16x16x32_bf16 v[64:67], v[148:151], v[156:159], v[64:67]
	v_mfma_f32_16x16x32_bf16 v[52:55], v[140:143], v[180:183], v[52:55]
	v_mfma_f32_16x16x32_bf16 v[48:51], v[148:151], v[180:183], v[48:51]
	v_mfma_f32_16x16x32_bf16 v[36:39], v[140:143], v[188:191], v[36:39]
	v_mfma_f32_16x16x32_bf16 v[32:35], v[148:151], v[188:191], v[32:35]
	v_mfma_f32_16x16x32_bf16 v[20:23], v[140:143], v[222:225], v[20:23]
	v_mfma_f32_16x16x32_bf16 v[16:19], v[148:151], v[222:225], v[16:19]
	v_mfma_f32_16x16x32_bf16 v[68:71], v[144:147], v[160:163], v[68:71]
	v_mfma_f32_16x16x32_bf16 v[64:67], v[152:155], v[160:163], v[64:67]
	v_mfma_f32_16x16x32_bf16 v[52:55], v[144:147], v[184:187], v[52:55]
	v_mfma_f32_16x16x32_bf16 v[48:51], v[152:155], v[184:187], v[48:51]
	v_mfma_f32_16x16x32_bf16 v[36:39], v[144:147], v[192:195], v[36:39]
	v_mfma_f32_16x16x32_bf16 v[32:35], v[152:155], v[192:195], v[32:35]
	v_mfma_f32_16x16x32_bf16 v[20:23], v[144:147], v[226:229], v[20:23]
	v_mfma_f32_16x16x32_bf16 v[16:19], v[152:155], v[226:229], v[16:19]
	s_setprio 0
	s_barrier
	s_add_u32 s56, s60, 0x100080
	s_addc_u32 s57, s61, 0
	s_add_i32 s12, s26, s65
	s_mov_b32 m0, s12
	s_nop 0
	global_load_lds_dwordx4 v0, s[56:57]
	s_add_i32 m0, s12, 0x2000
	s_nop 0
	global_load_lds_dwordx4 v2, s[56:57]
	s_waitcnt vmcnt(6)
	s_barrier
	s_setprio 1
	v_mfma_f32_16x16x32_bf16 v[60:63], v[230:233], v[156:159], v[60:63]
	v_mfma_f32_16x16x32_bf16 v[56:59], v[238:241], v[156:159], v[56:59]
	v_mfma_f32_16x16x32_bf16 v[44:47], v[230:233], v[180:183], v[44:47]
	v_mfma_f32_16x16x32_bf16 v[40:43], v[238:241], v[180:183], v[40:43]
	v_mfma_f32_16x16x32_bf16 v[28:31], v[230:233], v[188:191], v[28:31]
	v_mfma_f32_16x16x32_bf16 v[24:27], v[238:241], v[188:191], v[24:27]
	v_mfma_f32_16x16x32_bf16 v[12:15], v[230:233], v[222:225], v[12:15]
	v_mfma_f32_16x16x32_bf16 v[8:11], v[238:241], v[222:225], v[8:11]
	v_mfma_f32_16x16x32_bf16 v[60:63], v[234:237], v[160:163], v[60:63]
	v_mfma_f32_16x16x32_bf16 v[56:59], v[242:245], v[160:163], v[56:59]
	v_mfma_f32_16x16x32_bf16 v[44:47], v[234:237], v[184:187], v[44:47]
	v_mfma_f32_16x16x32_bf16 v[40:43], v[242:245], v[184:187], v[40:43]
	v_mfma_f32_16x16x32_bf16 v[28:31], v[234:237], v[192:195], v[28:31]
	v_mfma_f32_16x16x32_bf16 v[24:27], v[242:245], v[192:195], v[24:27]
	v_mfma_f32_16x16x32_bf16 v[12:15], v[234:237], v[226:229], v[12:15]
	v_mfma_f32_16x16x32_bf16 v[8:11], v[242:245], v[226:229], v[8:11]
	s_setprio 0
	s_add_i32 s79, s79, 2
	s_add_u32 s77, s77, 0x100
	s_addc_u32 s78, s78, 0
	s_cmp_gt_u32 s79, 61
	s_mov_b64 s[56:57], s[58:59]
	s_barrier
	s_cbranch_scc1 .LBB0_748

;     __device__ __forceinline__ void prep(int pm, int par, LAS unsigned char* lds) const { if (fold) prep_rowstats(stat, pm, par, lds); }
;     __device__ __forceinline__ void prep(int pm, int par, LAS unsigned char* lds) const { if (!ident) prep_rowstats(stat, pm, par, lds); }
;     __device__ __forceinline__ void prep(int pm, int par, LAS unsigned char* lds) const { prep_rowstats(stat, pm, par, lds); }
; #define G_STAGE(bufoff, gbase) do { _Pragma("unroll") for (int _i = 0; _i < 2; ++_i) \
;         __builtin_amdgcn_global_load_lds((const unsigned*)((const char*)(gbase) + voff[_i]), (LAS unsigned*)(lds + (bufoff) + ldsw + _i * 8192), 16, 0, 0); } while (0)
; #define G_LDA(dst, b, h) do { _Pragma("unroll") for (int m = 0; m < 4; ++m) _Pragma("unroll") for (int k = 0; k < 2; ++k) dst[m][k] = *(const LAS bf16x8*)(lds + G_SA(b, h) + aoff + m * 2048 + k * 1024); } while (0)
; #define G_LDB(dst, b, h) do { _Pragma("unroll") for (int n = 0; n < 2; ++n) _Pragma("unroll") for (int k = 0; k < 2; ++k) dst[n][k] = *(const LAS bf16x8*)(lds + G_SB(b, h) + boff + n * 2048 + k * 1024); } while (0)
; #define G_WAIT_L(n) asm volatile("s_waitcnt lgkmcnt(" #n ")" ::: "memory")
; #define G_BAR __builtin_amdgcn_s_barrier()
; #define G_SCHED __builtin_amdgcn_sched_barrier(0)
; template <class Epi>
; __device__ __forceinline__ void gemm_phase(LAS unsigned char* lds, const bf16_t* Ag, const bf16_t* Btg, const int K, const int nM, const int nN, const Epi& E) {
;     ...
;         for (int t = 0; t < nt; t += 2) {
;             const bool last = (t == nt - 2);
;             const char* a1 = cA + (size_t)(t + 1) * kstep;
;             const char* a2 = last ? nA : cA + (size_t)(t + 2) * kstep; const char* b2 = last ? nB : cB + (size_t)(t + 2) * kstep;
;             const char* a3 = a2 + kstep; const char* b3 = b2 + kstep;
;             if (last && has_next && pmn != pm) E.prep(pmn, par ^ 1, lds);
;             G_LDB(B0, 0, 0); G_SCHED; G_LDA(At, 0, 0); G_STAGE(G_SA(1, 1), a1 + hstep);
;             G_WAIT_L(8); G_BAR; G_WAIT_L(0); G_MMA(0, 0, At, B0); G_BAR; G_SCHED;
;             G_LDB(B1, 0, 1); G_STAGE(G_SB(0, 0), b2);
;             G_BAR; G_WAIT_L(0); G_MMA(0, 1, At, B1); G_BAR;
;             G_LDA(At, 0, 1); G_STAGE(G_SA(0, 0), a2);
;             G_BAR; G_WAIT_L(0); G_MMA(1, 0, At, B0); G_BAR; G_SCHED;
.LBB0_848:
	s_add_u32 s26, s50, 0xfffc0080
	s_addc_u32 s54, s51, -1
	s_and_b64 s[52:53], s[52:53], exec
	s_cselect_b32 s55, s54, s25
	s_cselect_b32 s54, s26, s24
	s_cselect_b32 s53, s71, s14
	s_cselect_b32 s52, s70, s15
	s_add_i32 s26, 0, 0x10000
	v_add_u32_e32 v129, s26, v179
	ds_read_b128 v[130:133], v129
	ds_read_b128 v[134:137], v129 offset:1024
	ds_read_b128 v[144:147], v129 offset:2048
	ds_read_b128 v[148:151], v129 offset:3072
	s_add_i32 m0, s60, 0xc000
	ds_read_b128 v[156:159], v222
	ds_read_b128 v[160:163], v222 offset:1024
	ds_read_b128 v[164:167], v222 offset:2048
	ds_read_b128 v[180:183], v222 offset:3072
	ds_read_b128 v[184:187], v222 offset:4096
	ds_read_b128 v[224:227], v222 offset:5120
	ds_read_b128 v[228:231], v222 offset:6144
	ds_read_b128 v[232:235], v222 offset:7168
	global_load_lds_dwordx4 v170, s[50:51]
	s_add_i32 m0, s60, 0xe000
	s_nop 0
	global_load_lds_dwordx4 v168, s[50:51]
	s_waitcnt lgkmcnt(8)
	s_barrier
	s_waitcnt lgkmcnt(0)
	s_setprio 1
	s_waitcnt lgkmcnt(0)
	v_mfma_f32_16x16x32_bf16 v[152:155], v[130:133], v[156:159], v[152:155]
	v_mfma_f32_16x16x32_bf16 v[138:141], v[144:147], v[156:159], v[140:143]
	v_mfma_f32_16x16x32_bf16 v[116:119], v[130:133], v[164:167], v[116:119]
	v_mfma_f32_16x16x32_bf16 v[112:115], v[144:147], v[164:167], v[112:115]
	v_mfma_f32_16x16x32_bf16 v[100:103], v[130:133], v[184:187], v[100:103]
	v_mfma_f32_16x16x32_bf16 v[96:99], v[144:147], v[184:187], v[96:99]
	v_mfma_f32_16x16x32_bf16 v[84:87], v[130:133], v[228:231], v[84:87]
	v_mfma_f32_16x16x32_bf16 v[80:83], v[144:147], v[228:231], v[80:83]
	v_mfma_f32_16x16x32_bf16 v[152:155], v[134:137], v[160:163], v[152:155]
	v_mfma_f32_16x16x32_bf16 v[138:141], v[148:151], v[160:163], v[138:141]
	v_mfma_f32_16x16x32_bf16 v[116:119], v[134:137], v[180:183], v[116:119]
	v_mfma_f32_16x16x32_bf16 v[112:115], v[148:151], v[180:183], v[112:115]
	v_mfma_f32_16x16x32_bf16 v[100:103], v[134:137], v[224:227], v[100:103]
	v_mfma_f32_16x16x32_bf16 v[96:99], v[148:151], v[224:227], v[96:99]
	v_mfma_f32_16x16x32_bf16 v[84:87], v[134:137], v[232:235], v[84:87]
	v_mfma_f32_16x16x32_bf16 v[80:83], v[148:151], v[232:235], v[80:83]
	s_setprio 0
	s_barrier
	s_add_i32 s73, 0, 0x14000
	s_add_i32 s26, s26, s59
	v_add_u32_e32 v129, s73, v179
	s_mov_b32 m0, s26
	ds_read_b128 v[236:239], v129
	ds_read_b128 v[240:243], v129 offset:1024
	ds_read_b128 v[244:247], v129 offset:2048
	ds_read_b128 v[248:251], v129 offset:3072
	global_load_lds_dwordx4 v0, s[52:53]
	s_add_i32 m0, s26, 0x2000
	s_nop 0
	global_load_lds_dwordx4 v2, s[52:53]
	s_barrier
	s_waitcnt lgkmcnt(0)
	s_setprio 1
	s_waitcnt lgkmcnt(0)
	v_mfma_f32_16x16x32_bf16 v[124:127], v[236:239], v[156:159], v[124:127]
	v_mfma_f32_16x16x32_bf16 v[120:123], v[244:247], v[156:159], v[120:123]
	v_mfma_f32_16x16x32_bf16 v[108:111], v[236:239], v[164:167], v[108:111]
	v_mfma_f32_16x16x32_bf16 v[104:107], v[244:247], v[164:167], v[104:107]
	v_mfma_f32_16x16x32_bf16 v[92:95], v[236:239], v[184:187], v[92:95]
	v_mfma_f32_16x16x32_bf16 v[88:91], v[244:247], v[184:187], v[88:91]
	v_mfma_f32_16x16x32_bf16 v[76:79], v[236:239], v[228:231], v[76:79]
	v_mfma_f32_16x16x32_bf16 v[72:75], v[244:247], v[228:231], v[72:75]
	v_mfma_f32_16x16x32_bf16 v[124:127], v[240:243], v[160:163], v[124:127]
	v_mfma_f32_16x16x32_bf16 v[120:123], v[248:251], v[160:163], v[120:123]
	v_mfma_f32_16x16x32_bf16 v[108:111], v[240:243], v[180:183], v[108:111]
	v_mfma_f32_16x16x32_bf16 v[104:107], v[248:251], v[180:183], v[104:107]
	v_mfma_f32_16x16x32_bf16 v[92:95], v[240:243], v[224:227], v[92:95]
	v_mfma_f32_16x16x32_bf16 v[88:91], v[248:251], v[224:227], v[88:91]
	v_mfma_f32_16x16x32_bf16 v[76:79], v[240:243], v[232:235], v[76:79]
	v_mfma_f32_16x16x32_bf16 v[72:75], v[248:251], v[232:235], v[72:75]
	s_setprio 0
	s_mov_b32 m0, s60
	s_add_u32 s76, s54, 0x80
	s_addc_u32 s77, s55, 0
	s_barrier
	ds_read_b128 v[156:159], v222 offset:16384
	ds_read_b128 v[160:163], v222 offset:17408
	ds_read_b128 v[164:167], v222 offset:18432
	ds_read_b128 v[180:183], v222 offset:19456
	ds_read_b128 v[184:187], v222 offset:20480
	ds_read_b128 v[224:227], v222 offset:21504
	ds_read_b128 v[228:231], v222 offset:22528
	ds_read_b128 v[232:235], v222 offset:23552
	global_load_lds_dwordx4 v0, s[54:55]
	s_add_u32 s76, s54, 0x80
	s_addc_u32 s77, s55, 0
	s_mov_b32 m0, s61
	s_nop 0
	global_load_lds_dwordx4 v2, s[54:55]
	s_barrier
	s_waitcnt lgkmcnt(0)
	s_setprio 1
	s_waitcnt lgkmcnt(0)
	v_mfma_f32_16x16x32_bf16 v[60:63], v[130:133], v[156:159], v[60:63]
	v_mfma_f32_16x16x32_bf16 v[56:59], v[144:147], v[156:159], v[56:59]
	v_mfma_f32_16x16x32_bf16 v[44:47], v[130:133], v[164:167], v[44:47]
	v_mfma_f32_16x16x32_bf16 v[40:43], v[144:147], v[164:167], v[40:43]
	v_mfma_f32_16x16x32_bf16 v[28:31], v[130:133], v[184:187], v[28:31]
	v_mfma_f32_16x16x32_bf16 v[24:27], v[144:147], v[184:187], v[24:27]
	v_mfma_f32_16x16x32_bf16 v[12:15], v[130:133], v[228:231], v[12:15]
	v_mfma_f32_16x16x32_bf16 v[8:11], v[144:147], v[228:231], v[8:11]
	v_mfma_f32_16x16x32_bf16 v[60:63], v[134:137], v[160:163], v[60:63]
	v_mfma_f32_16x16x32_bf16 v[56:59], v[148:151], v[160:163], v[56:59]
	v_mfma_f32_16x16x32_bf16 v[44:47], v[134:137], v[180:183], v[44:47]
	v_mfma_f32_16x16x32_bf16 v[40:43], v[148:151], v[180:183], v[40:43]
	v_mfma_f32_16x16x32_bf16 v[28:31], v[134:137], v[224:227], v[28:31]
	v_mfma_f32_16x16x32_bf16 v[24:27], v[148:151], v[224:227], v[24:27]
	v_mfma_f32_16x16x32_bf16 v[12:15], v[134:137], v[232:235], v[12:15]
	v_mfma_f32_16x16x32_bf16 v[8:11], v[148:151], v[232:235], v[8:11]
	s_setprio 0
	s_barrier
; #define G_STAGE(bufoff, gbase) do { _Pragma("unroll") for (int _i = 0; _i < 2; ++_i) \
;         __builtin_amdgcn_global_load_lds((const unsigned*)((const char*)(gbase) + voff[_i]), (LAS unsigned*)(lds + (bufoff) + ldsw + _i * 8192), 16, 0, 0); } while (0)
; #define G_LDA(dst, b, h) do { _Pragma("unroll") for (int m = 0; m < 4; ++m) _Pragma("unroll") for (int k = 0; k < 2; ++k) dst[m][k] = *(const LAS bf16x8*)(lds + G_SA(b, h) + aoff + m * 2048 + k * 1024); } while (0)
; #define G_LDB(dst, b, h) do { _Pragma("unroll") for (int n = 0; n < 2; ++n) _Pragma("unroll") for (int k = 0; k < 2; ++k) dst[n][k] = *(const LAS bf16x8*)(lds + G_SB(b, h) + boff + n * 2048 + k * 1024); } while (0)
; #define G_MMA(ai, bj, At, Bt) do { __builtin_amdgcn_s_setprio(1); _Pragma("unroll") for (int m = 0; m < 4; ++m) _Pragma("unroll") for (int n = 0; n < 2; ++n) _Pragma("unroll") for (int k = 0; k < 2; ++k) \
;         acc[ai][bj][m][n] = MFMA16(Bt[n][k], At[m][k], acc[ai][bj][m][n]); __builtin_amdgcn_s_setprio(0); } while (0)
; #define G_WAIT_V(n) asm volatile("s_waitcnt vmcnt(" #n ")" ::: "memory")
; #define G_WAIT_L(n) asm volatile("s_waitcnt lgkmcnt(" #n ")" ::: "memory")
; #define G_BAR __builtin_amdgcn_s_barrier()
; #define G_SCHED __builtin_amdgcn_sched_barrier(0)
; template <class Epi>
; __device__ __forceinline__ void gemm_phase(LAS unsigned char* lds, const bf16_t* Ag, const bf16_t* Btg, const int K, const int nM, const int nN, const Epi& E) {
;     ...
;             G_STAGE(G_SB(0, 1), b2 + hstep);
;             G_WAIT_V(6); G_BAR; G_MMA(1, 1, At, B1); G_BAR;
;             G_LDB(B0, 1, 0); G_SCHED; G_LDA(At, 1, 0); G_STAGE(G_SA(0, 1), a2 + hstep);
;             G_WAIT_L(8); G_BAR; G_WAIT_L(0); G_MMA(0, 0, At, B0); G_BAR; G_SCHED;
;             G_LDB(B1, 1, 1); G_STAGE(G_SB(1, 0), b3);
	s_add_u32 s74, s52, 0x40000
	s_addc_u32 s75, s53, 0
	s_add_i32 s26, s73, s59
	s_mov_b32 m0, s26
	s_nop 0
	global_load_lds_dwordx4 v0, s[74:75]
	s_add_i32 m0, s26, 0x2000
	s_nop 0
	global_load_lds_dwordx4 v2, s[74:75]
	s_waitcnt vmcnt(6)
	s_barrier
	s_setprio 1
	v_mfma_f32_16x16x32_bf16 v[68:71], v[236:239], v[156:159], v[68:71]
	v_mfma_f32_16x16x32_bf16 v[64:67], v[244:247], v[156:159], v[64:67]
	v_mfma_f32_16x16x32_bf16 v[52:55], v[236:239], v[164:167], v[52:55]
	v_mfma_f32_16x16x32_bf16 v[48:51], v[244:247], v[164:167], v[48:51]
	v_mfma_f32_16x16x32_bf16 v[36:39], v[236:239], v[184:187], v[36:39]
	v_mfma_f32_16x16x32_bf16 v[32:35], v[244:247], v[184:187], v[32:35]
	v_mfma_f32_16x16x32_bf16 v[20:23], v[236:239], v[228:231], v[20:23]
	v_mfma_f32_16x16x32_bf16 v[16:19], v[244:247], v[228:231], v[16:19]
	v_mfma_f32_16x16x32_bf16 v[68:71], v[240:243], v[160:163], v[68:71]
	v_mfma_f32_16x16x32_bf16 v[64:67], v[248:251], v[160:163], v[64:67]
	v_mfma_f32_16x16x32_bf16 v[52:55], v[240:243], v[180:183], v[52:55]
	v_mfma_f32_16x16x32_bf16 v[48:51], v[248:251], v[180:183], v[48:51]
	v_mfma_f32_16x16x32_bf16 v[36:39], v[240:243], v[224:227], v[36:39]
	v_mfma_f32_16x16x32_bf16 v[32:35], v[248:251], v[224:227], v[32:35]
	v_mfma_f32_16x16x32_bf16 v[20:23], v[240:243], v[232:235], v[20:23]
	v_mfma_f32_16x16x32_bf16 v[16:19], v[248:251], v[232:235], v[16:19]
	s_setprio 0
	s_add_i32 s26, 0, 0x18000
	v_add_u32_e32 v129, s26, v179
	s_barrier
	ds_read_b128 v[130:133], v129
	ds_read_b128 v[134:137], v129 offset:1024
	ds_read_b128 v[144:147], v129 offset:2048
	ds_read_b128 v[148:151], v129 offset:3072
	s_add_u32 s54, s54, 0x40000
	s_addc_u32 s55, s55, 0
	s_mov_b32 m0, s62
	ds_read_b128 v[156:159], v222 offset:32768
	ds_read_b128 v[160:163], v222 offset:33792
	ds_read_b128 v[164:167], v222 offset:34816
	ds_read_b128 v[180:183], v222 offset:35840
	ds_read_b128 v[184:187], v222 offset:36864
	ds_read_b128 v[224:227], v222 offset:37888
	ds_read_b128 v[228:231], v222 offset:38912
	ds_read_b128 v[232:235], v222 offset:39936
	global_load_lds_dwordx4 v0, s[54:55]
	s_mov_b32 m0, s63
	s_nop 0
	global_load_lds_dwordx4 v2, s[54:55]
	s_waitcnt lgkmcnt(8)
	s_barrier
	s_waitcnt lgkmcnt(0)
	s_setprio 1
	s_waitcnt lgkmcnt(0)
	v_mfma_f32_16x16x32_bf16 v[152:155], v[130:133], v[156:159], v[152:155]
	v_mfma_f32_16x16x32_bf16 v[138:141], v[144:147], v[156:159], v[138:141]
	v_mfma_f32_16x16x32_bf16 v[116:119], v[130:133], v[164:167], v[116:119]
	v_mfma_f32_16x16x32_bf16 v[112:115], v[144:147], v[164:167], v[112:115]
	v_mfma_f32_16x16x32_bf16 v[100:103], v[130:133], v[184:187], v[100:103]
	v_mfma_f32_16x16x32_bf16 v[96:99], v[144:147], v[184:187], v[96:99]
	v_mfma_f32_16x16x32_bf16 v[84:87], v[130:133], v[228:231], v[84:87]
	v_mfma_f32_16x16x32_bf16 v[80:83], v[144:147], v[228:231], v[80:83]
	v_mfma_f32_16x16x32_bf16 v[152:155], v[134:137], v[160:163], v[152:155]
	v_mfma_f32_16x16x32_bf16 v[140:143], v[148:151], v[160:163], v[138:141]
	v_mfma_f32_16x16x32_bf16 v[116:119], v[134:137], v[180:183], v[116:119]
	v_mfma_f32_16x16x32_bf16 v[112:115], v[148:151], v[180:183], v[112:115]
	v_mfma_f32_16x16x32_bf16 v[100:103], v[134:137], v[224:227], v[100:103]
	v_mfma_f32_16x16x32_bf16 v[96:99], v[148:151], v[224:227], v[96:99]
	v_mfma_f32_16x16x32_bf16 v[84:87], v[134:137], v[232:235], v[84:87]
	v_mfma_f32_16x16x32_bf16 v[80:83], v[148:151], v[232:235], v[80:83]
	s_setprio 0
	s_barrier
	s_add_i32 s54, 0, 0x1c000
	s_add_i32 s26, s26, s59
	v_add_u32_e32 v129, s54, v179
	s_mov_b32 m0, s26
	ds_read_b128 v[236:239], v129
	ds_read_b128 v[240:243], v129 offset:1024
	ds_read_b128 v[244:247], v129 offset:2048
	ds_read_b128 v[248:251], v129 offset:3072
	s_add_u32 s98, s52, 0x80
	s_addc_u32 s99, s53, 0
	global_load_lds_dwordx4 v0, s[98:99]
	s_add_i32 m0, s26, 0x2000
	s_nop 0
	s_add_u32 s98, s52, 0x80
	s_addc_u32 s99, s53, 0
	global_load_lds_dwordx4 v2, s[98:99]
	s_barrier
; #define G_STAGE(bufoff, gbase) do { _Pragma("unroll") for (int _i = 0; _i < 2; ++_i) \
;         __builtin_amdgcn_global_load_lds((const unsigned*)((const char*)(gbase) + voff[_i]), (LAS unsigned*)(lds + (bufoff) + ldsw + _i * 8192), 16, 0, 0); } while (0)
; #define G_LDA(dst, b, h) do { _Pragma("unroll") for (int m = 0; m < 4; ++m) _Pragma("unroll") for (int k = 0; k < 2; ++k) dst[m][k] = *(const LAS bf16x8*)(lds + G_SA(b, h) + aoff + m * 2048 + k * 1024); } while (0)
; #define G_MMA(ai, bj, At, Bt) do { __builtin_amdgcn_s_setprio(1); _Pragma("unroll") for (int m = 0; m < 4; ++m) _Pragma("unroll") for (int n = 0; n < 2; ++n) _Pragma("unroll") for (int k = 0; k < 2; ++k) \
;         acc[ai][bj][m][n] = MFMA16(Bt[n][k], At[m][k], acc[ai][bj][m][n]); __builtin_amdgcn_s_setprio(0); } while (0)
; #define G_WAIT_V(n) asm volatile("s_waitcnt vmcnt(" #n ")" ::: "memory")
; #define G_WAIT_L(n) asm volatile("s_waitcnt lgkmcnt(" #n ")" ::: "memory")
; #define G_BAR __builtin_amdgcn_s_barrier()
; #define G_SCHED __builtin_amdgcn_sched_barrier(0)
; template <class Epi>
; __device__ __forceinline__ void gemm_phase(LAS unsigned char* lds, const bf16_t* Ag, const bf16_t* Btg, const int K, const int nM, const int nN, const Epi& E) {
;     ...
;         for (int t = 0; t < nt; t += 2) {
;     ...
;             G_BAR; G_WAIT_L(0); G_MMA(0, 1, At, B1); G_BAR;
;             G_LDA(At, 1, 1); G_STAGE(G_SA(1, 0), a3);
;             G_BAR; G_WAIT_L(0); G_MMA(1, 0, At, B0); G_BAR; G_SCHED;
;             G_STAGE(G_SB(1, 1), b3 + hstep);
;             G_WAIT_V(6); G_BAR; G_MMA(1, 1, At, B1); G_BAR;
	s_waitcnt lgkmcnt(0)
	s_setprio 1
	s_waitcnt lgkmcnt(0)
	v_mfma_f32_16x16x32_bf16 v[124:127], v[236:239], v[156:159], v[124:127]
	v_mfma_f32_16x16x32_bf16 v[120:123], v[244:247], v[156:159], v[120:123]
	v_mfma_f32_16x16x32_bf16 v[108:111], v[236:239], v[164:167], v[108:111]
	v_mfma_f32_16x16x32_bf16 v[104:107], v[244:247], v[164:167], v[104:107]
	v_mfma_f32_16x16x32_bf16 v[92:95], v[236:239], v[184:187], v[92:95]
	v_mfma_f32_16x16x32_bf16 v[88:91], v[244:247], v[184:187], v[88:91]
	v_mfma_f32_16x16x32_bf16 v[76:79], v[236:239], v[228:231], v[76:79]
	v_mfma_f32_16x16x32_bf16 v[72:75], v[244:247], v[228:231], v[72:75]
	v_mfma_f32_16x16x32_bf16 v[124:127], v[240:243], v[160:163], v[124:127]
	v_mfma_f32_16x16x32_bf16 v[120:123], v[248:251], v[160:163], v[120:123]
	v_mfma_f32_16x16x32_bf16 v[108:111], v[240:243], v[180:183], v[108:111]
	v_mfma_f32_16x16x32_bf16 v[104:107], v[248:251], v[180:183], v[104:107]
	v_mfma_f32_16x16x32_bf16 v[92:95], v[240:243], v[224:227], v[92:95]
	v_mfma_f32_16x16x32_bf16 v[88:91], v[248:251], v[224:227], v[88:91]
	v_mfma_f32_16x16x32_bf16 v[76:79], v[240:243], v[232:235], v[76:79]
	v_mfma_f32_16x16x32_bf16 v[72:75], v[248:251], v[232:235], v[72:75]
	s_setprio 0
	s_mov_b32 m0, s64
	s_barrier
	ds_read_b128 v[156:159], v222 offset:49152
	ds_read_b128 v[160:163], v222 offset:50176
	ds_read_b128 v[164:167], v222 offset:51200
	ds_read_b128 v[180:183], v222 offset:52224
	ds_read_b128 v[184:187], v222 offset:53248
	ds_read_b128 v[224:227], v222 offset:54272
	ds_read_b128 v[228:231], v222 offset:55296
	ds_read_b128 v[232:235], v222 offset:56320
	global_load_lds_dwordx4 v0, s[76:77]
	s_mov_b32 m0, s65
	s_nop 0
	global_load_lds_dwordx4 v2, s[76:77]
	s_barrier
	s_waitcnt lgkmcnt(0)
	s_setprio 1
	s_waitcnt lgkmcnt(0)
	v_mfma_f32_16x16x32_bf16 v[60:63], v[130:133], v[156:159], v[60:63]
	v_mfma_f32_16x16x32_bf16 v[56:59], v[144:147], v[156:159], v[56:59]
	v_mfma_f32_16x16x32_bf16 v[44:47], v[130:133], v[164:167], v[44:47]
	v_mfma_f32_16x16x32_bf16 v[40:43], v[144:147], v[164:167], v[40:43]
	v_mfma_f32_16x16x32_bf16 v[28:31], v[130:133], v[184:187], v[28:31]
	v_mfma_f32_16x16x32_bf16 v[24:27], v[144:147], v[184:187], v[24:27]
	v_mfma_f32_16x16x32_bf16 v[12:15], v[130:133], v[228:231], v[12:15]
	v_mfma_f32_16x16x32_bf16 v[8:11], v[144:147], v[228:231], v[8:11]
	v_mfma_f32_16x16x32_bf16 v[60:63], v[134:137], v[160:163], v[60:63]
	v_mfma_f32_16x16x32_bf16 v[56:59], v[148:151], v[160:163], v[56:59]
	v_mfma_f32_16x16x32_bf16 v[44:47], v[134:137], v[180:183], v[44:47]
	v_mfma_f32_16x16x32_bf16 v[40:43], v[148:151], v[180:183], v[40:43]
	v_mfma_f32_16x16x32_bf16 v[28:31], v[134:137], v[224:227], v[28:31]
	v_mfma_f32_16x16x32_bf16 v[24:27], v[148:151], v[224:227], v[24:27]
	v_mfma_f32_16x16x32_bf16 v[12:15], v[134:137], v[232:235], v[12:15]
	v_mfma_f32_16x16x32_bf16 v[8:11], v[148:151], v[232:235], v[8:11]
	s_setprio 0
	s_barrier
	s_add_u32 s52, s52, 0x40080
	s_addc_u32 s53, s53, 0
	s_add_i32 s26, s54, s59
	s_mov_b32 m0, s26
	s_nop 0
	global_load_lds_dwordx4 v0, s[52:53]
	s_add_i32 m0, s26, 0x2000
	s_nop 0
	global_load_lds_dwordx4 v2, s[52:53]
	s_waitcnt vmcnt(6)
	s_barrier
	s_setprio 1
	v_mfma_f32_16x16x32_bf16 v[68:71], v[236:239], v[156:159], v[68:71]
	v_mfma_f32_16x16x32_bf16 v[64:67], v[244:247], v[156:159], v[64:67]
	v_mfma_f32_16x16x32_bf16 v[52:55], v[236:239], v[164:167], v[52:55]
	v_mfma_f32_16x16x32_bf16 v[48:51], v[244:247], v[164:167], v[48:51]
	v_mfma_f32_16x16x32_bf16 v[36:39], v[236:239], v[184:187], v[36:39]
	v_mfma_f32_16x16x32_bf16 v[32:35], v[244:247], v[184:187], v[32:35]
	v_mfma_f32_16x16x32_bf16 v[20:23], v[236:239], v[228:231], v[20:23]
	v_mfma_f32_16x16x32_bf16 v[16:19], v[244:247], v[228:231], v[16:19]
	v_mfma_f32_16x16x32_bf16 v[68:71], v[240:243], v[160:163], v[68:71]
	v_mfma_f32_16x16x32_bf16 v[64:67], v[248:251], v[160:163], v[64:67]
	v_mfma_f32_16x16x32_bf16 v[52:55], v[240:243], v[180:183], v[52:55]
	v_mfma_f32_16x16x32_bf16 v[48:51], v[248:251], v[180:183], v[48:51]
	v_mfma_f32_16x16x32_bf16 v[36:39], v[240:243], v[224:227], v[36:39]
	v_mfma_f32_16x16x32_bf16 v[32:35], v[248:251], v[224:227], v[32:35]
	v_mfma_f32_16x16x32_bf16 v[20:23], v[240:243], v[232:235], v[20:23]
	v_mfma_f32_16x16x32_bf16 v[16:19], v[248:251], v[232:235], v[16:19]
	s_setprio 0
	s_add_i32 s72, s72, 2
	s_add_u32 s70, s70, 0x100
	s_addc_u32 s71, s71, 0
	s_add_u32 s50, s50, 0x100
	s_addc_u32 s51, s51, 0
	s_cmp_gt_u32 s72, 13
	s_barrier
	s_cbranch_scc1 .LBB0_852
